# LN epilogues: counter-free exchange of row statistics: self-validating tagged 16-byte records (slot-major, contiguous per wave) polled by the consumers; no barriers/atomics in the epilogue
# speedup vs baseline: 1.0751x; 1.0259x over previous
.LBB0_94:
	s_mul_hi_u32 s23, s19, 0xaaaaaaab
	s_lshr_b32 s23, s23, 1
	s_mul_i32 s23, s23, 0x24000
	s_waitcnt lgkmcnt(0)
	v_mfma_f32_16x16x32_bf16 v[66:69], v[22:25], v[26:29], v[66:69]
	v_add_u32_e32 v222, s13, v113
	s_mul_hi_u32 s27, s14, 0xaaaaaaab
	s_lshr_b32 s27, s27, 1
	v_mfma_f32_16x16x32_bf16 v[62:65], v[18:21], v[26:29], v[62:65]
	s_mul_i32 s27, s27, 0x24000
	v_subrev_u32_e32 v182, s27, v126
	v_subrev_u32_e32 v191, s27, v127
	v_mfma_f32_16x16x32_bf16 v[58:61], v[10:13], v[26:29], v[58:61]
	v_subrev_u32_e32 v201, s27, v128
	v_mfma_f32_16x16x32_bf16 v[54:57], v[6:9], v[26:29], v[54:57]
	v_subrev_u32_e32 v26, s23, v125
	v_mfma_f32_16x16x32_bf16 v[50:53], v[22:25], v[14:17], v[50:53]
	v_mfma_f32_16x16x32_bf16 v[46:49], v[18:21], v[14:17], v[46:49]
	v_mfma_f32_16x16x32_bf16 v[42:45], v[10:13], v[14:17], v[42:45]
	v_mfma_f32_16x16x32_bf16 v[38:41], v[6:9], v[14:17], v[38:41]
	v_subrev_u32_e32 v14, s23, v129
	v_add_u32_e32 v16, v222, v26
	v_add_u32_e32 v14, v222, v14
	v_mfma_f32_16x16x32_bf16 v[34:37], v[22:25], v[30:33], v[34:37]
	v_subrev_u32_e32 v15, s27, v130
	v_mfma_f32_16x16x32_bf16 v[86:89], v[22:25], v[2:5], v[86:89]
	ds_read_b128 v[22:25], v16
	ds_read_b128 v[174:177], v16 offset:2048
	ds_read_b128 v[178:181], v16 offset:4096
	ds_read_b128 v[202:205], v16 offset:6144
	ds_read_b128 v[206:209], v14 offset:32768
	ds_read_b128 v[210:213], v14 offset:34816
	ds_read_b128 v[214:217], v14 offset:36864
	ds_read_b128 v[218:221], v14 offset:38912
	v_mfma_f32_16x16x32_bf16 v[74:77], v[18:21], v[30:33], v[74:77]
	v_mfma_f32_16x16x32_bf16 v[70:73], v[10:13], v[30:33], v[70:73]
	v_mfma_f32_16x16x32_bf16 v[78:81], v[6:9], v[30:33], v[78:81]
	v_mfma_f32_16x16x32_bf16 v[94:97], v[18:21], v[2:5], v[94:97]
	v_mfma_f32_16x16x32_bf16 v[90:93], v[10:13], v[2:5], v[90:93]
	v_mfma_f32_16x16x32_bf16 v[82:85], v[6:9], v[2:5], v[82:85]
	s_add_i32 s23, s6, 4
	s_mul_i32 s27, s23, 0xab
	s_bfe_u32 s27, s27, 0x70009
	s_mul_i32 s27, s27, 3
	s_sub_i32 s23, s23, s27
	s_and_b32 s23, s23, 0xff
	s_mul_i32 s23, s23, 0xc000
	s_waitcnt vmcnt(6)
	v_add_u32_e32 v2, v222, v15
	v_add_u32_e32 v6, v222, v201
	s_waitcnt lgkmcnt(0)
	v_mfma_f32_16x16x32_bf16 v[66:69], v[206:209], v[174:177], v[66:69]
	s_mov_b64 s[46:47], 0xbdd8180
	s_add_i32 s27, s23, s8
	s_waitcnt lgkmcnt(0)
	v_mfma_f32_16x16x32_bf16 v[62:65], v[210:213], v[174:177], v[62:65]
	s_barrier
	ds_read_b128 v[30:33], v2
	ds_read_b128 v[26:29], v2 offset:2048
	ds_read_b128 v[14:17], v2 offset:4096
	ds_read_b128 v[2:5], v2 offset:6144
	v_mfma_f32_16x16x32_bf16 v[58:61], v[214:217], v[174:177], v[58:61]
	v_add_u32_e32 v7, v222, v191
	s_mov_b32 m0, s27
	s_add_i32 s23, s23, s9
	v_mfma_f32_16x16x32_bf16 v[54:57], v[218:221], v[174:177], v[54:57]
	v_lshl_add_u64 v[174:175], v[108:109], 0, v[98:99]
	v_lshl_add_u64 v[176:177], v[174:175], 0, s[46:47]
	s_mov_b64 s[46:47], 0xbddc180
	v_mfma_f32_16x16x32_bf16 v[34:37], v[206:209], v[22:25], v[34:37]
	s_add_i32 s19, s19, 1
	v_mfma_f32_16x16x32_bf16 v[74:77], v[210:213], v[22:25], v[74:77]
	v_mfma_f32_16x16x32_bf16 v[70:73], v[214:217], v[22:25], v[70:73]
	v_mfma_f32_16x16x32_bf16 v[78:81], v[218:221], v[22:25], v[78:81]
	ds_read_b128 v[22:25], v6
	ds_read_b128 v[18:21], v7
	v_add_u32_e32 v6, v222, v182
	ds_read_b128 v[10:13], v6
	ds_read_b128 v[6:9], v6 offset:2048
	global_load_lds_dwordx4 v[176:177], off
	v_lshl_add_u64 v[176:177], v[174:175], 0, s[46:47]
	s_add_i32 m0, s27, 0x400
	s_mov_b64 s[46:47], 0xbde0180
	global_load_lds_dwordx4 v[176:177], off
	v_lshl_add_u64 v[176:177], v[174:175], 0, s[46:47]
	s_add_i32 m0, s27, 0x800
	s_mov_b64 s[46:47], 0xbde4180
	global_load_lds_dwordx4 v[176:177], off
	v_lshl_add_u64 v[174:175], v[174:175], 0, s[46:47]
	s_add_i32 m0, s27, 0xc00
	s_mov_b64 s[46:47], 0x1b00180
	global_load_lds_dwordx4 v[174:175], off
	v_lshl_add_u64 v[174:175], v[110:111], 0, v[98:99]
	v_lshl_add_u64 v[176:177], v[174:175], 0, s[46:47]
	s_add_i32 m0, s23, 0x8000
	s_mov_b64 s[46:47], 0x1b04180
	global_load_lds_dwordx4 v[176:177], off
	v_lshl_add_u64 v[174:175], v[174:175], 0, s[46:47]
	s_add_i32 m0, s23, 0x8400
	v_mfma_f32_16x16x32_bf16 v[50:53], v[206:209], v[178:181], v[50:53]
	global_load_lds_dwordx4 v[174:175], off
	v_mfma_f32_16x16x32_bf16 v[46:49], v[210:213], v[178:181], v[46:49]
	v_mfma_f32_16x16x32_bf16 v[42:45], v[214:217], v[178:181], v[42:45]
	v_mfma_f32_16x16x32_bf16 v[38:41], v[218:221], v[178:181], v[38:41]
	v_mfma_f32_16x16x32_bf16 v[86:89], v[206:209], v[202:205], v[86:89]
	v_mfma_f32_16x16x32_bf16 v[94:97], v[210:213], v[202:205], v[94:97]
	v_mfma_f32_16x16x32_bf16 v[90:93], v[214:217], v[202:205], v[90:93]
	v_mfma_f32_16x16x32_bf16 v[82:85], v[218:221], v[202:205], v[82:85]
	s_add_i32 s6, s6, 1
	s_add_i32 s13, s13, 0xc000
	s_add_i32 s14, s14, 1
	v_lshl_add_u64 v[108:109], v[108:109], 0, s[2:3]
	s_cmp_eq_u32 s13, 0x9c000
	v_lshl_add_u64 v[110:111], v[110:111], 0, s[2:3]
	s_cbranch_scc0 .LBB0_94
	s_waitcnt lgkmcnt(0)
	v_mfma_f32_16x16x32_bf16 v[34:37], v[22:25], v[30:33], v[34:37]
	v_mfma_f32_16x16x32_bf16 v[74:77], v[18:21], v[30:33], v[74:77]
	v_mfma_f32_16x16x32_bf16 v[70:73], v[10:13], v[30:33], v[70:73]
	v_mfma_f32_16x16x32_bf16 v[30:33], v[6:9], v[30:33], v[78:81]
	v_mfma_f32_16x16x32_bf16 v[66:69], v[22:25], v[26:29], v[66:69]
	v_mfma_f32_16x16x32_bf16 v[62:65], v[18:21], v[26:29], v[62:65]
	v_mfma_f32_16x16x32_bf16 v[58:61], v[10:13], v[26:29], v[58:61]
	v_mfma_f32_16x16x32_bf16 v[26:29], v[6:9], v[26:29], v[54:57]
	v_mfma_f32_16x16x32_bf16 v[50:53], v[22:25], v[14:17], v[50:53]
	v_mfma_f32_16x16x32_bf16 v[46:49], v[18:21], v[14:17], v[46:49]
	v_mfma_f32_16x16x32_bf16 v[42:45], v[10:13], v[14:17], v[42:45]
	v_mfma_f32_16x16x32_bf16 v[14:17], v[6:9], v[14:17], v[38:41]
	v_mfma_f32_16x16x32_bf16 v[22:25], v[22:25], v[2:5], v[86:89]
	s_nop 1
	ds_read_b128 v[38:41], v131
	ds_read_b128 v[54:57], v132 offset:2048
	ds_read_b128 v[78:81], v132 offset:4096
	ds_read_b128 v[86:89], v132 offset:6144
	v_mfma_f32_16x16x32_bf16 v[18:21], v[18:21], v[2:5], v[94:97]
	v_mfma_f32_16x16x32_bf16 v[10:13], v[10:13], v[2:5], v[90:93]
	s_nop 2
	ds_read_b128 v[90:93], v133 offset:32768
	ds_read_b128 v[94:97], v134 offset:34816
	ds_read_b128 v[108:111], v134 offset:36864
	ds_read_b128 v[174:177], v134 offset:38912
	v_mfma_f32_16x16x32_bf16 v[2:5], v[6:9], v[2:5], v[82:85]
	s_waitcnt lgkmcnt(0)
	v_mfma_f32_16x16x32_bf16 v[6:9], v[90:93], v[38:41], v[34:37]
	s_waitcnt vmcnt(6)
	s_waitcnt lgkmcnt(0)
	s_barrier
	v_mfma_f32_16x16x32_bf16 v[34:37], v[94:97], v[38:41], v[74:77]
	v_mfma_f32_16x16x32_bf16 v[70:73], v[108:111], v[38:41], v[70:73]
	v_mfma_f32_16x16x32_bf16 v[30:33], v[174:177], v[38:41], v[30:33]
	v_mfma_f32_16x16x32_bf16 v[38:41], v[90:93], v[54:57], v[66:69]
	v_mfma_f32_16x16x32_bf16 v[62:65], v[94:97], v[54:57], v[62:65]
	v_mfma_f32_16x16x32_bf16 v[58:61], v[108:111], v[54:57], v[58:61]
	v_mfma_f32_16x16x32_bf16 v[26:29], v[174:177], v[54:57], v[26:29]
	v_add_u32_e32 v54, v124, v115
	ds_read_b128 v[54:57], v54
	ds_read_b128 v[66:69], v135 offset:2048
	v_mfma_f32_16x16x32_bf16 v[50:53], v[90:93], v[78:81], v[50:53]
	v_mfma_f32_16x16x32_bf16 v[46:49], v[94:97], v[78:81], v[46:49]
	v_mfma_f32_16x16x32_bf16 v[42:45], v[108:111], v[78:81], v[42:45]
	v_mfma_f32_16x16x32_bf16 v[22:25], v[90:93], v[86:89], v[22:25]
	v_add_u32_e32 v90, 0x20800, v164
	v_mfma_f32_16x16x32_bf16 v[18:21], v[94:97], v[86:89], v[18:21]
	v_add_u32_e32 v94, 0x21000, v164
	v_mfma_f32_16x16x32_bf16 v[10:13], v[108:111], v[86:89], v[10:13]
	v_add_u32_e32 v108, 0x21800, v164
	v_mfma_f32_16x16x32_bf16 v[14:17], v[174:177], v[78:81], v[14:17]
	ds_read_b128 v[74:77], v135 offset:4096
	ds_read_b128 v[78:81], v135 offset:6144
	ds_read_b128 v[82:85], v163
	ds_read_b128 v[90:93], v90
	ds_read_b128 v[94:97], v94
	ds_read_b128 v[108:111], v108
	v_mfma_f32_16x16x32_bf16 v[2:5], v[174:177], v[86:89], v[2:5]
	s_waitcnt lgkmcnt(0)
	v_mfma_f32_16x16x32_bf16 v[6:9], v[82:85], v[54:57], v[6:9]
	v_mfma_f32_16x16x32_bf16 v[34:37], v[90:93], v[54:57], v[34:37]
	v_mfma_f32_16x16x32_bf16 v[70:73], v[94:97], v[54:57], v[70:73]
	v_mfma_f32_16x16x32_bf16 v[30:33], v[108:111], v[54:57], v[30:33]
	v_mfma_f32_16x16x32_bf16 v[54:57], v[90:93], v[66:69], v[62:65]
	s_nop 2
	v_add_u32_e32 v62, v124, v119
	v_mfma_f32_16x16x32_bf16 v[38:41], v[82:85], v[66:69], v[38:41]
	v_mfma_f32_16x16x32_bf16 v[58:61], v[94:97], v[66:69], v[58:61]
	v_mfma_f32_16x16x32_bf16 v[26:29], v[108:111], v[66:69], v[26:29]
	v_mfma_f32_16x16x32_bf16 v[50:53], v[82:85], v[74:77], v[50:53]
	v_mfma_f32_16x16x32_bf16 v[46:49], v[90:93], v[74:77], v[46:49]
	v_mfma_f32_16x16x32_bf16 v[42:45], v[94:97], v[74:77], v[42:45]
	v_mfma_f32_16x16x32_bf16 v[14:17], v[108:111], v[74:77], v[14:17]
	v_mfma_f32_16x16x32_bf16 v[22:25], v[82:85], v[78:81], v[22:25]
	ds_read_b128 v[62:65], v62
	ds_read_b128 v[66:69], v165
	ds_read_b128 v[74:77], v166
	ds_read_b128 v[82:85], v167
	v_mfma_f32_16x16x32_bf16 v[18:21], v[90:93], v[78:81], v[18:21]
	v_mfma_f32_16x16x32_bf16 v[10:13], v[94:97], v[78:81], v[10:13]
	ds_read_b128 v[86:89], v168
	ds_read_b128 v[90:93], v169
	ds_read_b128 v[94:97], v170
	ds_read_b128 v[174:177], v171
	v_mfma_f32_16x16x32_bf16 v[2:5], v[108:111], v[78:81], v[2:5]
	s_waitcnt vmcnt(0)
	s_waitcnt lgkmcnt(0)
	v_mfma_f32_16x16x32_bf16 v[6:9], v[86:89], v[62:65], v[6:9]
	s_waitcnt lgkmcnt(0)
	s_barrier
	v_mfma_f32_16x16x32_bf16 v[34:37], v[90:93], v[62:65], v[34:37]
	v_mfma_f32_16x16x32_bf16 v[70:73], v[94:97], v[62:65], v[70:73]
	v_mfma_f32_16x16x32_bf16 v[30:33], v[174:177], v[62:65], v[30:33]
	v_mfma_f32_16x16x32_bf16 v[38:41], v[86:89], v[66:69], v[38:41]
	v_mfma_f32_16x16x32_bf16 v[54:57], v[90:93], v[66:69], v[54:57]
	v_mfma_f32_16x16x32_bf16 v[58:61], v[94:97], v[66:69], v[58:61]
	v_mfma_f32_16x16x32_bf16 v[26:29], v[174:177], v[66:69], v[26:29]
	v_mfma_f32_16x16x32_bf16 v[50:53], v[86:89], v[74:77], v[50:53]
	v_mfma_f32_16x16x32_bf16 v[46:49], v[90:93], v[74:77], v[46:49]
	v_mfma_f32_16x16x32_bf16 v[42:45], v[94:97], v[74:77], v[42:45]
	v_mfma_f32_16x16x32_bf16 v[14:17], v[174:177], v[74:77], v[14:17]
	ds_read_b128 v[62:65], v164 offset:38912
	ds_read_b128 v[66:69], v164 offset:36864
	ds_read_b128 v[74:77], v164 offset:34816
	ds_read_b128 v[78:81], v161 offset:32768
	v_mfma_f32_16x16x32_bf16 v[22:25], v[86:89], v[82:85], v[22:25]
	v_mfma_f32_16x16x32_bf16 v[18:21], v[90:93], v[82:85], v[18:21]
	v_mfma_f32_16x16x32_bf16 v[10:13], v[94:97], v[82:85], v[10:13]
	ds_read_b128 v[86:89], v173 offset:6144
	ds_read_b128 v[90:93], v173 offset:4096
	ds_read_b128 v[94:97], v173 offset:2048
	ds_read_b128 v[108:111], v172
	v_mfma_f32_16x16x32_bf16 v[2:5], v[174:177], v[82:85], v[2:5]
	s_waitcnt lgkmcnt(0)
	v_mfma_f32_16x16x32_bf16 v[38:41], v[78:81], v[94:97], v[38:41]
	v_add_u32_e32 v82, v114, v119
	v_add_u32_e32 v172, v118, v119
	v_mfma_f32_16x16x32_bf16 v[54:57], v[74:77], v[94:97], v[54:57]
	v_mfma_f32_16x16x32_bf16 v[58:61], v[66:69], v[94:97], v[58:61]
	v_mfma_f32_16x16x32_bf16 v[26:29], v[62:65], v[94:97], v[26:29]
	v_add_u32_e32 v94, v117, v119
	v_mfma_f32_16x16x32_bf16 v[50:53], v[78:81], v[90:93], v[50:53]
	v_mfma_f32_16x16x32_bf16 v[46:49], v[74:77], v[90:93], v[46:49]
	v_mfma_f32_16x16x32_bf16 v[42:45], v[66:69], v[90:93], v[42:45]
	v_mfma_f32_16x16x32_bf16 v[14:17], v[62:65], v[90:93], v[14:17]
	v_add_u32_e32 v90, v116, v119
	v_mfma_f32_16x16x32_bf16 v[6:9], v[78:81], v[108:111], v[6:9]
	v_mfma_f32_16x16x32_bf16 v[34:37], v[74:77], v[108:111], v[34:37]
	v_mfma_f32_16x16x32_bf16 v[70:73], v[66:69], v[108:111], v[70:73]
	v_mfma_f32_16x16x32_bf16 v[30:33], v[62:65], v[108:111], v[30:33]
	v_mfma_f32_16x16x32_bf16 v[78:81], v[78:81], v[86:89], v[22:25]
	s_nop 2
	ds_read_b128 v[22:25], v82
	ds_read_b128 v[82:85], v90 offset:2048
	v_mfma_f32_16x16x32_bf16 v[74:77], v[74:77], v[86:89], v[18:21]
	s_nop 2
	ds_read_b128 v[18:21], v90 offset:4096
	ds_read_b128 v[90:93], v90 offset:6144
	v_mfma_f32_16x16x32_bf16 v[66:69], v[66:69], v[86:89], v[10:13]
	s_nop 2
	ds_read_b128 v[10:13], v94 offset:32768
	ds_read_b128 v[94:97], v172 offset:34816
	ds_read_b128 v[108:111], v172 offset:36864
	ds_read_b128 v[172:175], v172 offset:38912
	v_mfma_f32_16x16x32_bf16 v[2:5], v[62:65], v[86:89], v[2:5]
	s_waitcnt vmcnt(0)
	s_waitcnt lgkmcnt(0)
	v_mfma_f32_16x16x32_bf16 v[2:5], v[172:175], v[90:93], v[2:5]
	s_waitcnt lgkmcnt(0)
	s_barrier
	v_mfma_f32_16x16x32_bf16 v[62:65], v[10:13], v[22:25], v[6:9]
	v_mfma_f32_16x16x32_bf16 v[86:89], v[94:97], v[22:25], v[34:37]
	v_mfma_f32_16x16x32_bf16 v[70:73], v[108:111], v[22:25], v[70:73]
	v_mfma_f32_16x16x32_bf16 v[176:179], v[172:175], v[22:25], v[30:33]
	v_mfma_f32_16x16x32_bf16 v[202:205], v[10:13], v[82:85], v[38:41]
	v_mfma_f32_16x16x32_bf16 v[54:57], v[94:97], v[82:85], v[54:57]
	v_mfma_f32_16x16x32_bf16 v[58:61], v[108:111], v[82:85], v[58:61]
	v_mfma_f32_16x16x32_bf16 v[34:37], v[172:175], v[82:85], v[26:29]
	v_mfma_f32_16x16x32_bf16 v[30:33], v[10:13], v[18:21], v[50:53]
	v_mfma_f32_16x16x32_bf16 v[26:29], v[94:97], v[18:21], v[46:49]
	v_mfma_f32_16x16x32_bf16 v[22:25], v[108:111], v[18:21], v[42:45]
	v_mfma_f32_16x16x32_bf16 v[18:21], v[172:175], v[18:21], v[14:17]
	v_mfma_f32_16x16x32_bf16 v[14:17], v[10:13], v[90:93], v[78:81]
	v_mfma_f32_16x16x32_bf16 v[10:13], v[94:97], v[90:93], v[74:77]
	v_mfma_f32_16x16x32_bf16 v[6:9], v[108:111], v[90:93], v[66:69]
	s_mul_hi_i32 s64, s60, 0x2aaaaaab
	s_lshr_b32 s65, s64, 31
	s_ashr_i32 s64, s64, 2
	s_add_i32 s6, s64, s65
	s_mul_i32 s64, s6, 24
	s_sub_i32 s13, s60, s64
	v_readfirstlane_b32 s64, v137
	s_lshr_b32 s64, s64, 6
	s_and_b32 s14, s64, 1
	s_lshr_b32 s64, s64, 1
	s_lshl_b32 s64, s64, 6
	s_lshl_b32 s36, s13, 8
	s_add_i32 s36, s36, s64
	s_lshl_b32 s37, s6, 7
	s_lshl_b32 s64, s14, 6
	s_add_i32 s37, s37, s64
	s_add_i32 s64, s36, 0xfffff000
	s_ashr_i32 s64, s64, 10
	s_add_i32 s64, s64, 1
	s_cmpk_lt_i32 s36, 0x1000
	s_cselect_b32 s52, 0, s64
	v_readlane_b32 s53, v255, 40
	v_and_b32_e32 v250, 63, v137
	v_and_b32_e32 v251, 15, v250
	v_lshrrev_b32_e32 v252, 4, v250
	s_mul_i32 s64, s53, 3
	s_add_i32 s64, s64, s52
	s_mul_i32 s64, s64, 0x6000
	s_add_u32 s22, s94, 0x6300000
	s_addc_u32 s23, s95, 0
	s_add_u32 s22, s22, s64
	s_addc_u32 s23, s23, 0
	s_add_u32 s26, s94, 0x6348000
	s_addc_u32 s27, s95, 0
	v_add_u32_e32 v242, s36, v251
	v_lshlrev_b32_e32 v242, 12, v242
	s_lshl_b32 s64, s37, 2
	v_lshl_add_u32 v242, v252, 4, v242
	v_add_u32_e32 v242, s64, v242
	s_add_i32 s65, s37, 2048
	s_lshl_b32 s65, s65, 2
	v_lshl_add_u32 v246, v252, 4, s65
	v_add_u32_e32 v243, 0x10000, v242
	v_add_u32_e32 v244, 0x20000, v242
	v_add_u32_e32 v245, 0x30000, v242
	global_load_dwordx4 v[226:229], v246, s[22:23]
	global_load_dwordx4 v[230:233], v246, s[22:23] offset:64
	global_load_dwordx4 v[234:237], v246, s[22:23] offset:128
	global_load_dwordx4 v[238:241], v246, s[22:23] offset:192
	global_load_dwordx4 v[38:41], v242, s[26:27]
	global_load_dwordx4 v[42:45], v242, s[26:27] offset:64
	global_load_dwordx4 v[46:49], v242, s[26:27] offset:128
	global_load_dwordx4 v[50:53], v242, s[26:27] offset:192
	global_load_dwordx4 v[66:69], v243, s[26:27]
	global_load_dwordx4 v[74:77], v243, s[26:27] offset:64
	global_load_dwordx4 v[78:81], v243, s[26:27] offset:128
	global_load_dwordx4 v[82:85], v243, s[26:27] offset:192
	global_load_dwordx4 v[90:93], v244, s[26:27]
	global_load_dwordx4 v[94:97], v244, s[26:27] offset:64
	global_load_dwordx4 v[108:111], v244, s[26:27] offset:128
	global_load_dwordx4 v[172:175], v244, s[26:27] offset:192
	global_load_dwordx4 v[206:209], v245, s[26:27]
	global_load_dwordx4 v[210:213], v245, s[26:27] offset:64
	global_load_dwordx4 v[214:217], v245, s[26:27] offset:128
	global_load_dwordx4 v[218:221], v245, s[26:27] offset:192
	v_mov_b32_e32 v248, 0x3fd744fd
	v_mov_b32_e32 v249, 0x3fd744fd
	s_waitcnt vmcnt(12)
	v_pk_mul_f32 v[38:39], v[38:39], v[248:249]
	v_pk_mul_f32 v[40:41], v[40:41], v[248:249]
	v_pk_fma_f32 v[62:63], v[62:63], v[226:227], v[38:39]
	v_pk_fma_f32 v[64:65], v[64:65], v[228:229], v[40:41]
	v_pk_mul_f32 v[42:43], v[42:43], v[248:249]
	v_pk_mul_f32 v[44:45], v[44:45], v[248:249]
	v_pk_fma_f32 v[86:87], v[86:87], v[230:231], v[42:43]
	v_pk_fma_f32 v[88:89], v[88:89], v[232:233], v[44:45]
	v_pk_mul_f32 v[46:47], v[46:47], v[248:249]
	v_pk_mul_f32 v[48:49], v[48:49], v[248:249]
	v_pk_fma_f32 v[70:71], v[70:71], v[234:235], v[46:47]
	v_pk_fma_f32 v[72:73], v[72:73], v[236:237], v[48:49]
	v_pk_mul_f32 v[50:51], v[50:51], v[248:249]
	v_pk_mul_f32 v[52:53], v[52:53], v[248:249]
	v_pk_fma_f32 v[176:177], v[176:177], v[238:239], v[50:51]
	v_pk_fma_f32 v[178:179], v[178:179], v[240:241], v[52:53]
	s_waitcnt vmcnt(8)
	v_pk_mul_f32 v[66:67], v[66:67], v[248:249]
	v_pk_mul_f32 v[68:69], v[68:69], v[248:249]
	v_pk_fma_f32 v[202:203], v[202:203], v[226:227], v[66:67]
	v_pk_fma_f32 v[204:205], v[204:205], v[228:229], v[68:69]
	v_pk_mul_f32 v[74:75], v[74:75], v[248:249]
	v_pk_mul_f32 v[76:77], v[76:77], v[248:249]
	v_pk_fma_f32 v[54:55], v[54:55], v[230:231], v[74:75]
	v_pk_fma_f32 v[56:57], v[56:57], v[232:233], v[76:77]
	v_pk_mul_f32 v[78:79], v[78:79], v[248:249]
	v_pk_mul_f32 v[80:81], v[80:81], v[248:249]
	v_pk_fma_f32 v[58:59], v[58:59], v[234:235], v[78:79]
	v_pk_fma_f32 v[60:61], v[60:61], v[236:237], v[80:81]
	v_pk_mul_f32 v[82:83], v[82:83], v[248:249]
	v_pk_mul_f32 v[84:85], v[84:85], v[248:249]
	v_pk_fma_f32 v[34:35], v[34:35], v[238:239], v[82:83]
	v_pk_fma_f32 v[36:37], v[36:37], v[240:241], v[84:85]
	s_waitcnt vmcnt(4)
	v_pk_mul_f32 v[90:91], v[90:91], v[248:249]
	v_pk_mul_f32 v[92:93], v[92:93], v[248:249]
	v_pk_fma_f32 v[30:31], v[30:31], v[226:227], v[90:91]
	v_pk_fma_f32 v[32:33], v[32:33], v[228:229], v[92:93]
	v_pk_mul_f32 v[94:95], v[94:95], v[248:249]
	v_pk_mul_f32 v[96:97], v[96:97], v[248:249]
	v_pk_fma_f32 v[26:27], v[26:27], v[230:231], v[94:95]
	v_pk_fma_f32 v[28:29], v[28:29], v[232:233], v[96:97]
	v_pk_mul_f32 v[108:109], v[108:109], v[248:249]
	v_pk_mul_f32 v[110:111], v[110:111], v[248:249]
	v_pk_fma_f32 v[22:23], v[22:23], v[234:235], v[108:109]
	v_pk_fma_f32 v[24:25], v[24:25], v[236:237], v[110:111]
	v_pk_mul_f32 v[172:173], v[172:173], v[248:249]
	v_pk_mul_f32 v[174:175], v[174:175], v[248:249]
	v_pk_fma_f32 v[18:19], v[18:19], v[238:239], v[172:173]
	v_pk_fma_f32 v[20:21], v[20:21], v[240:241], v[174:175]
	s_waitcnt vmcnt(0)
	v_pk_mul_f32 v[206:207], v[206:207], v[248:249]
	v_pk_mul_f32 v[208:209], v[208:209], v[248:249]
	v_pk_fma_f32 v[14:15], v[14:15], v[226:227], v[206:207]
	v_pk_fma_f32 v[16:17], v[16:17], v[228:229], v[208:209]
	v_pk_mul_f32 v[210:211], v[210:211], v[248:249]
	v_pk_mul_f32 v[212:213], v[212:213], v[248:249]
	v_pk_fma_f32 v[10:11], v[10:11], v[230:231], v[210:211]
	v_pk_fma_f32 v[12:13], v[12:13], v[232:233], v[212:213]
	v_pk_mul_f32 v[214:215], v[214:215], v[248:249]
	v_pk_mul_f32 v[216:217], v[216:217], v[248:249]
	v_pk_fma_f32 v[6:7], v[6:7], v[234:235], v[214:215]
	v_pk_fma_f32 v[8:9], v[8:9], v[236:237], v[216:217]
	v_pk_mul_f32 v[218:219], v[218:219], v[248:249]
	v_pk_mul_f32 v[220:221], v[220:221], v[248:249]
	v_pk_fma_f32 v[2:3], v[2:3], v[238:239], v[218:219]
	v_pk_fma_f32 v[4:5], v[4:5], v[240:241], v[220:221]
	v_pk_mul_f32 v[208:209], v[62:63], v[62:63]
	v_pk_add_f32 v[206:207], v[62:63], v[64:65]
	v_pk_fma_f32 v[208:209], v[64:65], v[64:65], v[208:209]
	v_pk_add_f32 v[206:207], v[206:207], v[86:87]
	v_pk_fma_f32 v[208:209], v[86:87], v[86:87], v[208:209]
	v_pk_add_f32 v[206:207], v[206:207], v[88:89]
	v_pk_fma_f32 v[208:209], v[88:89], v[88:89], v[208:209]
	v_pk_add_f32 v[206:207], v[206:207], v[70:71]
	v_pk_fma_f32 v[208:209], v[70:71], v[70:71], v[208:209]
	v_pk_add_f32 v[206:207], v[206:207], v[72:73]
	v_pk_fma_f32 v[208:209], v[72:73], v[72:73], v[208:209]
	v_pk_add_f32 v[206:207], v[206:207], v[176:177]
	v_pk_fma_f32 v[208:209], v[176:177], v[176:177], v[208:209]
	v_pk_add_f32 v[206:207], v[206:207], v[178:179]
	v_pk_fma_f32 v[208:209], v[178:179], v[178:179], v[208:209]
	v_add_f32_e32 v206, v206, v207
	v_add_f32_e32 v208, v208, v209
	v_pk_mul_f32 v[212:213], v[202:203], v[202:203]
	v_pk_add_f32 v[210:211], v[202:203], v[204:205]
	v_pk_fma_f32 v[212:213], v[204:205], v[204:205], v[212:213]
	v_pk_add_f32 v[210:211], v[210:211], v[54:55]
	v_pk_fma_f32 v[212:213], v[54:55], v[54:55], v[212:213]
	v_pk_add_f32 v[210:211], v[210:211], v[56:57]
	v_pk_fma_f32 v[212:213], v[56:57], v[56:57], v[212:213]
	v_pk_add_f32 v[210:211], v[210:211], v[58:59]
	v_pk_fma_f32 v[212:213], v[58:59], v[58:59], v[212:213]
	v_pk_add_f32 v[210:211], v[210:211], v[60:61]
	v_pk_fma_f32 v[212:213], v[60:61], v[60:61], v[212:213]
	v_pk_add_f32 v[210:211], v[210:211], v[34:35]
	v_pk_fma_f32 v[212:213], v[34:35], v[34:35], v[212:213]
	v_pk_add_f32 v[210:211], v[210:211], v[36:37]
	v_pk_fma_f32 v[212:213], v[36:37], v[36:37], v[212:213]
	v_add_f32_e32 v210, v210, v211
	v_add_f32_e32 v212, v212, v213
	v_pk_mul_f32 v[216:217], v[30:31], v[30:31]
	v_pk_add_f32 v[214:215], v[30:31], v[32:33]
	v_pk_fma_f32 v[216:217], v[32:33], v[32:33], v[216:217]
	v_pk_add_f32 v[214:215], v[214:215], v[26:27]
	v_pk_fma_f32 v[216:217], v[26:27], v[26:27], v[216:217]
	v_pk_add_f32 v[214:215], v[214:215], v[28:29]
	v_pk_fma_f32 v[216:217], v[28:29], v[28:29], v[216:217]
	v_pk_add_f32 v[214:215], v[214:215], v[22:23]
	v_pk_fma_f32 v[216:217], v[22:23], v[22:23], v[216:217]
	v_pk_add_f32 v[214:215], v[214:215], v[24:25]
	v_pk_fma_f32 v[216:217], v[24:25], v[24:25], v[216:217]
	v_pk_add_f32 v[214:215], v[214:215], v[18:19]
	v_pk_fma_f32 v[216:217], v[18:19], v[18:19], v[216:217]
	v_pk_add_f32 v[214:215], v[214:215], v[20:21]
	v_pk_fma_f32 v[216:217], v[20:21], v[20:21], v[216:217]
	v_add_f32_e32 v214, v214, v215
	v_add_f32_e32 v216, v216, v217
	v_pk_mul_f32 v[220:221], v[14:15], v[14:15]
	v_pk_add_f32 v[218:219], v[14:15], v[16:17]
	v_pk_fma_f32 v[220:221], v[16:17], v[16:17], v[220:221]
	v_pk_add_f32 v[218:219], v[218:219], v[10:11]
	v_pk_fma_f32 v[220:221], v[10:11], v[10:11], v[220:221]
	v_pk_add_f32 v[218:219], v[218:219], v[12:13]
	v_pk_fma_f32 v[220:221], v[12:13], v[12:13], v[220:221]
	v_pk_add_f32 v[218:219], v[218:219], v[6:7]
	v_pk_fma_f32 v[220:221], v[6:7], v[6:7], v[220:221]
	v_pk_add_f32 v[218:219], v[218:219], v[8:9]
	v_pk_fma_f32 v[220:221], v[8:9], v[8:9], v[220:221]
	v_pk_add_f32 v[218:219], v[218:219], v[2:3]
	v_pk_fma_f32 v[220:221], v[2:3], v[2:3], v[220:221]
	v_pk_add_f32 v[218:219], v[218:219], v[4:5]
	v_pk_fma_f32 v[220:221], v[4:5], v[4:5], v[220:221]
	v_add_f32_e32 v218, v218, v219
	v_add_f32_e32 v220, v220, v221
	s_nop 1
	v_permlane16_swap_b32_e32 v206, v210
	v_permlane16_swap_b32_e32 v214, v218
	v_permlane16_swap_b32_e32 v208, v212
	v_permlane16_swap_b32_e32 v216, v220
	v_add_f32_e32 v206, v206, v210
	v_add_f32_e32 v214, v214, v218
	v_add_f32_e32 v208, v208, v212
	v_add_f32_e32 v216, v216, v220
	s_nop 1
	v_permlane32_swap_b32_e32 v206, v214
	v_permlane32_swap_b32_e32 v208, v216
	v_add_f32_e32 v248, v206, v214
	v_add_f32_e32 v249, v208, v216
	s_lshl_b32 s64, s53, 1
	s_add_i32 s64, s64, 0x5a5a5a00
	v_mov_b32_e32 v218, v248
	v_mov_b32_e32 v219, s64
	v_mov_b32_e32 v220, v249
	v_mov_b32_e32 v221, s64
	v_mov_b32_e32 v249, s64
	s_add_u32 s44, s94, 0xc9d8000
	s_addc_u32 s45, s95, 0
	v_add_u32_e32 v247, s36, v250
	v_lshlrev_b32_e32 v247, 4, v247
	s_lshl_b32 s65, s6, 1
	s_add_i32 s65, s65, s14
	s_mul_i32 s65, s65, 0x18000
	v_add_u32_e32 v246, s65, v247
	global_store_dwordx4 v246, v[218:221], s[44:45] sc1
	v_readlane_b32 s46, v253, 11
	v_readlane_b32 s47, v253, 12
	v_readlane_b32 s48, v253, 13
	v_readlane_b32 s49, v253, 14
	s_lshl_b32 s64, s53, 10
	s_add_i32 s64, s64, s37
	s_lshl_b32 s64, s64, 2
	v_lshl_add_u32 v222, v252, 4, s64
	s_nop 3
	global_load_dwordx4 v[66:69], v222, s[46:47]
	global_load_dwordx4 v[74:77], v222, s[46:47] offset:64
	global_load_dwordx4 v[78:81], v222, s[46:47] offset:128
	global_load_dwordx4 v[82:85], v222, s[46:47] offset:192
	global_load_dwordx4 v[90:93], v222, s[48:49]
	global_load_dwordx4 v[94:97], v222, s[48:49] offset:64
	global_load_dwordx4 v[108:111], v222, s[48:49] offset:128
	global_load_dwordx4 v[172:175], v222, s[48:49] offset:192
	s_add_i32 s64, s37, 3072
	s_lshl_b32 s64, s64, 2
	v_lshl_add_u32 v222, v252, 4, s64
	v_add_u32_e32 v246, 0x1000, v222
	global_load_dwordx4 v[38:41], v222, s[22:23]
	global_load_dwordx4 v[42:45], v222, s[22:23] offset:64
	global_load_dwordx4 v[46:49], v222, s[22:23] offset:128
	global_load_dwordx4 v[50:53], v222, s[22:23] offset:192
	s_mov_b32 s65, 0x40000
.Lln1_poll0:
	global_load_dwordx4 v[226:229], v247, s[44:45] sc1
	v_add_u32_e32 v251, 0x18000, v247
	global_load_dwordx4 v[230:233], v251, s[44:45] sc1
	v_add_u32_e32 v251, 0x30000, v247
	global_load_dwordx4 v[234:237], v251, s[44:45] sc1
	v_add_u32_e32 v251, 0x48000, v247
	global_load_dwordx4 v[238:241], v251, s[44:45] sc1
	v_add_u32_e32 v251, 0x60000, v247
	global_load_dwordx4 v[206:209], v251, s[44:45] sc1
	v_add_u32_e32 v251, 0x78000, v247
	global_load_dwordx4 v[210:213], v251, s[44:45] sc1
	v_add_u32_e32 v251, 0x90000, v247
	global_load_dwordx4 v[214:217], v251, s[44:45] sc1
	v_add_u32_e32 v251, 0xa8000, v247
	global_load_dwordx4 v[218:221], v251, s[44:45] sc1
	s_waitcnt vmcnt(0)
	v_xor_b32_e32 v248, v249, v227
	v_xor_b32_e32 v222, v249, v229
	v_xor_b32_e32 v251, v249, v231
	v_or_b32_e32 v248, v248, v251
	v_xor_b32_e32 v251, v249, v233
	v_or_b32_e32 v222, v222, v251
	v_xor_b32_e32 v251, v249, v235
	v_or_b32_e32 v248, v248, v251
	v_xor_b32_e32 v251, v249, v237
	v_or_b32_e32 v222, v222, v251
	v_xor_b32_e32 v251, v249, v239
	v_or_b32_e32 v248, v248, v251
	v_xor_b32_e32 v251, v249, v241
	v_or_b32_e32 v222, v222, v251
	v_xor_b32_e32 v251, v249, v207
	v_or_b32_e32 v248, v248, v251
	v_xor_b32_e32 v251, v249, v209
	v_or_b32_e32 v222, v222, v251
	v_xor_b32_e32 v251, v249, v211
	v_or_b32_e32 v248, v248, v251
	v_xor_b32_e32 v251, v249, v213
	v_or_b32_e32 v222, v222, v251
	v_xor_b32_e32 v251, v249, v215
	v_or_b32_e32 v248, v248, v251
	v_xor_b32_e32 v251, v249, v217
	v_or_b32_e32 v222, v222, v251
	v_xor_b32_e32 v251, v249, v219
	v_or_b32_e32 v248, v248, v251
	v_xor_b32_e32 v251, v249, v221
	v_or_b32_e32 v222, v222, v251
	v_or_b32_e32 v248, v248, v222
	v_cmp_ne_u32_e32 vcc, 0, v248
	s_cbranch_vccz .Lln1_pok0
	s_sleep 2
	s_add_i32 s65, s65, -1
	s_cmp_lg_u32 s65, 0
	s_cbranch_scc1 .Lln1_poll0
.Lln1_pok0:
	v_add_f32_e32 v250, 0, v226
	v_add_f32_e32 v252, 0, v228
	v_add_f32_e32 v250, v250, v230
	v_add_f32_e32 v252, v252, v232
	v_add_f32_e32 v250, v250, v234
	v_add_f32_e32 v252, v252, v236
	v_add_f32_e32 v250, v250, v238
	v_add_f32_e32 v252, v252, v240
	v_add_f32_e32 v250, v250, v206
	v_add_f32_e32 v252, v252, v208
	v_add_f32_e32 v250, v250, v210
	v_add_f32_e32 v252, v252, v212
	v_add_f32_e32 v250, v250, v214
	v_add_f32_e32 v252, v252, v216
	v_add_f32_e32 v250, v250, v218
	v_add_f32_e32 v252, v252, v220
	s_mov_b32 s65, 0x40000
.Lln1_poll1:
	v_add_u32_e32 v251, 0xc0000, v247
	global_load_dwordx4 v[226:229], v251, s[44:45] sc1
	v_add_u32_e32 v251, 0xd8000, v247
	global_load_dwordx4 v[230:233], v251, s[44:45] sc1
	v_add_u32_e32 v251, 0xf0000, v247
	global_load_dwordx4 v[234:237], v251, s[44:45] sc1
	v_add_u32_e32 v251, 0x108000, v247
	global_load_dwordx4 v[238:241], v251, s[44:45] sc1
	v_add_u32_e32 v251, 0x120000, v247
	global_load_dwordx4 v[206:209], v251, s[44:45] sc1
	v_add_u32_e32 v251, 0x138000, v247
	global_load_dwordx4 v[210:213], v251, s[44:45] sc1
	v_add_u32_e32 v251, 0x150000, v247
	global_load_dwordx4 v[214:217], v251, s[44:45] sc1
	v_add_u32_e32 v251, 0x168000, v247
	global_load_dwordx4 v[218:221], v251, s[44:45] sc1
	s_waitcnt vmcnt(0)
	v_xor_b32_e32 v248, v249, v227
	v_xor_b32_e32 v222, v249, v229
	v_xor_b32_e32 v251, v249, v231
	v_or_b32_e32 v248, v248, v251
	v_xor_b32_e32 v251, v249, v233
	v_or_b32_e32 v222, v222, v251
	v_xor_b32_e32 v251, v249, v235
	v_or_b32_e32 v248, v248, v251
	v_xor_b32_e32 v251, v249, v237
	v_or_b32_e32 v222, v222, v251
	v_xor_b32_e32 v251, v249, v239
	v_or_b32_e32 v248, v248, v251
	v_xor_b32_e32 v251, v249, v241
	v_or_b32_e32 v222, v222, v251
	v_xor_b32_e32 v251, v249, v207
	v_or_b32_e32 v248, v248, v251
	v_xor_b32_e32 v251, v249, v209
	v_or_b32_e32 v222, v222, v251
	v_xor_b32_e32 v251, v249, v211
	v_or_b32_e32 v248, v248, v251
	v_xor_b32_e32 v251, v249, v213
	v_or_b32_e32 v222, v222, v251
	v_xor_b32_e32 v251, v249, v215
	v_or_b32_e32 v248, v248, v251
	v_xor_b32_e32 v251, v249, v217
	v_or_b32_e32 v222, v222, v251
	v_xor_b32_e32 v251, v249, v219
	v_or_b32_e32 v248, v248, v251
	v_xor_b32_e32 v251, v249, v221
	v_or_b32_e32 v222, v222, v251
	v_or_b32_e32 v248, v248, v222
	v_cmp_ne_u32_e32 vcc, 0, v248
	s_cbranch_vccz .Lln1_pok1
	s_sleep 2
	s_add_i32 s65, s65, -1
	s_cmp_lg_u32 s65, 0
	s_cbranch_scc1 .Lln1_poll1
.Lln1_pok1:
	v_add_f32_e32 v250, v250, v226
	v_add_f32_e32 v252, v252, v228
	v_add_f32_e32 v250, v250, v230
	v_add_f32_e32 v252, v252, v232
	v_add_f32_e32 v250, v250, v234
	v_add_f32_e32 v252, v252, v236
	v_add_f32_e32 v250, v250, v238
	v_add_f32_e32 v252, v252, v240
	v_add_f32_e32 v250, v250, v206
	v_add_f32_e32 v252, v252, v208
	v_add_f32_e32 v250, v250, v210
	v_add_f32_e32 v252, v252, v212
	v_add_f32_e32 v250, v250, v214
	v_add_f32_e32 v252, v252, v216
	v_add_f32_e32 v250, v250, v218
	v_add_f32_e32 v252, v252, v220
	global_load_dwordx4 v[226:229], v246, s[22:23]
	global_load_dwordx4 v[230:233], v246, s[22:23] offset:64
	global_load_dwordx4 v[234:237], v246, s[22:23] offset:128
	global_load_dwordx4 v[238:241], v246, s[22:23] offset:192
	v_mov_b32_e32 v206, v250
	v_mov_b32_e32 v207, v252
	v_mul_f32_e32 v208, 0x3a800000, v206
	v_mul_f32_e32 v209, v208, v208
	v_mov_b32_e32 v216, 0x3a800000
	v_fma_f32 v209, v207, v216, -v209
	v_max_f32_e32 v209, 0, v209
	v_add_f32_e32 v209, 0x3727c5ac, v209
	v_rsq_f32_e32 v209, v209
	v_mov_b32_e32 v210, v208
	v_mov_b32_e32 v211, v208
	v_mov_b32_e32 v214, v209
	v_mov_b32_e32 v215, v209
	s_nop 1
	v_permlane16_swap_b32_e32 v210, v211
	v_permlane16_swap_b32_e32 v214, v215
	v_mov_b32_e32 v212, v210
	v_mov_b32_e32 v213, v211
	v_mov_b32_e32 v216, v214
	v_mov_b32_e32 v217, v215
	s_nop 1
	v_permlane32_swap_b32_e32 v210, v212
	v_permlane32_swap_b32_e32 v211, v213
	v_permlane32_swap_b32_e32 v214, v216
	v_permlane32_swap_b32_e32 v215, v217
	v_sub_f32_e32 v62, v62, v210
	v_sub_f32_e32 v63, v63, v210
	v_sub_f32_e32 v64, v64, v210
	v_sub_f32_e32 v65, v65, v210
	v_mul_f32_e32 v62, v214, v62
	v_mul_f32_e32 v63, v214, v63
	v_mul_f32_e32 v64, v214, v64
	v_mul_f32_e32 v65, v214, v65
	v_fma_f32 v62, v66, v62, v90
	v_fma_f32 v63, v67, v63, v91
	v_fma_f32 v64, v68, v64, v92
	v_fma_f32 v65, v69, v65, v93
	global_store_dwordx4 v242, v[62:65], s[26:27]
	v_sub_f32_e32 v86, v86, v210
	v_sub_f32_e32 v87, v87, v210
	v_sub_f32_e32 v88, v88, v210
	v_sub_f32_e32 v89, v89, v210
	v_mul_f32_e32 v86, v214, v86
	v_mul_f32_e32 v87, v214, v87
	v_mul_f32_e32 v88, v214, v88
	v_mul_f32_e32 v89, v214, v89
	v_fma_f32 v86, v74, v86, v94
	v_fma_f32 v87, v75, v87, v95
	v_fma_f32 v88, v76, v88, v96
	v_fma_f32 v89, v77, v89, v97
	global_store_dwordx4 v242, v[86:89], s[26:27] offset:64
	v_sub_f32_e32 v70, v70, v210
	v_sub_f32_e32 v71, v71, v210
	v_sub_f32_e32 v72, v72, v210
	v_sub_f32_e32 v73, v73, v210
	v_mul_f32_e32 v70, v214, v70
	v_mul_f32_e32 v71, v214, v71
	v_mul_f32_e32 v72, v214, v72
	v_mul_f32_e32 v73, v214, v73
	v_fma_f32 v70, v78, v70, v108
	v_fma_f32 v71, v79, v71, v109
	v_fma_f32 v72, v80, v72, v110
	v_fma_f32 v73, v81, v73, v111
	global_store_dwordx4 v242, v[70:73], s[26:27] offset:128
	v_sub_f32_e32 v176, v176, v210
	v_sub_f32_e32 v177, v177, v210
	v_sub_f32_e32 v178, v178, v210
	v_sub_f32_e32 v179, v179, v210
	v_mul_f32_e32 v176, v214, v176
	v_mul_f32_e32 v177, v214, v177
	v_mul_f32_e32 v178, v214, v178
	v_mul_f32_e32 v179, v214, v179
	v_fma_f32 v176, v82, v176, v172
	v_fma_f32 v177, v83, v177, v173
	v_fma_f32 v178, v84, v178, v174
	v_fma_f32 v179, v85, v179, v175
	global_store_dwordx4 v242, v[176:179], s[26:27] offset:192
	v_sub_f32_e32 v202, v202, v211
	v_sub_f32_e32 v203, v203, v211
	v_sub_f32_e32 v204, v204, v211
	v_sub_f32_e32 v205, v205, v211
	v_mul_f32_e32 v202, v215, v202
	v_mul_f32_e32 v203, v215, v203
	v_mul_f32_e32 v204, v215, v204
	v_mul_f32_e32 v205, v215, v205
	v_fma_f32 v202, v66, v202, v90
	v_fma_f32 v203, v67, v203, v91
	v_fma_f32 v204, v68, v204, v92
	v_fma_f32 v205, v69, v205, v93
	global_store_dwordx4 v243, v[202:205], s[26:27]
	v_sub_f32_e32 v54, v54, v211
	v_sub_f32_e32 v55, v55, v211
	v_sub_f32_e32 v56, v56, v211
	v_sub_f32_e32 v57, v57, v211
	v_mul_f32_e32 v54, v215, v54
	v_mul_f32_e32 v55, v215, v55
	v_mul_f32_e32 v56, v215, v56
	v_mul_f32_e32 v57, v215, v57
	v_fma_f32 v54, v74, v54, v94
	v_fma_f32 v55, v75, v55, v95
	v_fma_f32 v56, v76, v56, v96
	v_fma_f32 v57, v77, v57, v97
	global_store_dwordx4 v243, v[54:57], s[26:27] offset:64
	v_sub_f32_e32 v58, v58, v211
	v_sub_f32_e32 v59, v59, v211
	v_sub_f32_e32 v60, v60, v211
	v_sub_f32_e32 v61, v61, v211
	v_mul_f32_e32 v58, v215, v58
	v_mul_f32_e32 v59, v215, v59
	v_mul_f32_e32 v60, v215, v60
	v_mul_f32_e32 v61, v215, v61
	v_fma_f32 v58, v78, v58, v108
	v_fma_f32 v59, v79, v59, v109
	v_fma_f32 v60, v80, v60, v110
	v_fma_f32 v61, v81, v61, v111
	global_store_dwordx4 v243, v[58:61], s[26:27] offset:128
	v_sub_f32_e32 v34, v34, v211
	v_sub_f32_e32 v35, v35, v211
	v_sub_f32_e32 v36, v36, v211
	v_sub_f32_e32 v37, v37, v211
	v_mul_f32_e32 v34, v215, v34
	v_mul_f32_e32 v35, v215, v35
	v_mul_f32_e32 v36, v215, v36
	v_mul_f32_e32 v37, v215, v37
	v_fma_f32 v34, v82, v34, v172
	v_fma_f32 v35, v83, v35, v173
	v_fma_f32 v36, v84, v36, v174
	v_fma_f32 v37, v85, v37, v175
	global_store_dwordx4 v243, v[34:37], s[26:27] offset:192
	v_sub_f32_e32 v30, v30, v212
	v_sub_f32_e32 v31, v31, v212
	v_sub_f32_e32 v32, v32, v212
	v_sub_f32_e32 v33, v33, v212
	v_mul_f32_e32 v30, v216, v30
	v_mul_f32_e32 v31, v216, v31
	v_mul_f32_e32 v32, v216, v32
	v_mul_f32_e32 v33, v216, v33
	v_fma_f32 v30, v66, v30, v90
	v_fma_f32 v31, v67, v31, v91
	v_fma_f32 v32, v68, v32, v92
	v_fma_f32 v33, v69, v33, v93
	global_store_dwordx4 v244, v[30:33], s[26:27]
	v_sub_f32_e32 v26, v26, v212
	v_sub_f32_e32 v27, v27, v212
	v_sub_f32_e32 v28, v28, v212
	v_sub_f32_e32 v29, v29, v212
	v_mul_f32_e32 v26, v216, v26
	v_mul_f32_e32 v27, v216, v27
	v_mul_f32_e32 v28, v216, v28
	v_mul_f32_e32 v29, v216, v29
	v_fma_f32 v26, v74, v26, v94
	v_fma_f32 v27, v75, v27, v95
	v_fma_f32 v28, v76, v28, v96
	v_fma_f32 v29, v77, v29, v97
	global_store_dwordx4 v244, v[26:29], s[26:27] offset:64
	v_sub_f32_e32 v22, v22, v212
	v_sub_f32_e32 v23, v23, v212
	v_sub_f32_e32 v24, v24, v212
	v_sub_f32_e32 v25, v25, v212
	v_mul_f32_e32 v22, v216, v22
	v_mul_f32_e32 v23, v216, v23
	v_mul_f32_e32 v24, v216, v24
	v_mul_f32_e32 v25, v216, v25
	v_fma_f32 v22, v78, v22, v108
	v_fma_f32 v23, v79, v23, v109
	v_fma_f32 v24, v80, v24, v110
	v_fma_f32 v25, v81, v25, v111
	global_store_dwordx4 v244, v[22:25], s[26:27] offset:128
	v_sub_f32_e32 v18, v18, v212
	v_sub_f32_e32 v19, v19, v212
	v_sub_f32_e32 v20, v20, v212
	v_sub_f32_e32 v21, v21, v212
	v_mul_f32_e32 v18, v216, v18
	v_mul_f32_e32 v19, v216, v19
	v_mul_f32_e32 v20, v216, v20
	v_mul_f32_e32 v21, v216, v21
	v_fma_f32 v18, v82, v18, v172
	v_fma_f32 v19, v83, v19, v173
	v_fma_f32 v20, v84, v20, v174
	v_fma_f32 v21, v85, v21, v175
	global_store_dwordx4 v244, v[18:21], s[26:27] offset:192
	v_sub_f32_e32 v14, v14, v213
	v_sub_f32_e32 v15, v15, v213
	v_sub_f32_e32 v16, v16, v213
	v_sub_f32_e32 v17, v17, v213
	v_mul_f32_e32 v14, v217, v14
	v_mul_f32_e32 v15, v217, v15
	v_mul_f32_e32 v16, v217, v16
	v_mul_f32_e32 v17, v217, v17
	v_fma_f32 v14, v66, v14, v90
	v_fma_f32 v15, v67, v15, v91
	v_fma_f32 v16, v68, v16, v92
	v_fma_f32 v17, v69, v17, v93
	global_store_dwordx4 v245, v[14:17], s[26:27]
	v_sub_f32_e32 v10, v10, v213
	v_sub_f32_e32 v11, v11, v213
	v_sub_f32_e32 v12, v12, v213
	v_sub_f32_e32 v13, v13, v213
	v_mul_f32_e32 v10, v217, v10
	v_mul_f32_e32 v11, v217, v11
	v_mul_f32_e32 v12, v217, v12
	v_mul_f32_e32 v13, v217, v13
	v_fma_f32 v10, v74, v10, v94
	v_fma_f32 v11, v75, v11, v95
	v_fma_f32 v12, v76, v12, v96
	v_fma_f32 v13, v77, v13, v97
	global_store_dwordx4 v245, v[10:13], s[26:27] offset:64
	v_sub_f32_e32 v6, v6, v213
	v_sub_f32_e32 v7, v7, v213
	v_sub_f32_e32 v8, v8, v213
	v_sub_f32_e32 v9, v9, v213
	v_mul_f32_e32 v6, v217, v6
	v_mul_f32_e32 v7, v217, v7
	v_mul_f32_e32 v8, v217, v8
	v_mul_f32_e32 v9, v217, v9
	v_fma_f32 v6, v78, v6, v108
	v_fma_f32 v7, v79, v7, v109
	v_fma_f32 v8, v80, v8, v110
	v_fma_f32 v9, v81, v9, v111
	global_store_dwordx4 v245, v[6:9], s[26:27] offset:128
	v_sub_f32_e32 v2, v2, v213
	v_sub_f32_e32 v3, v3, v213
	v_sub_f32_e32 v4, v4, v213
	v_sub_f32_e32 v5, v5, v213
	v_mul_f32_e32 v2, v217, v2
	v_mul_f32_e32 v3, v217, v3
	v_mul_f32_e32 v4, v217, v4
	v_mul_f32_e32 v5, v217, v5
	v_fma_f32 v2, v82, v2, v172
	v_fma_f32 v3, v83, v3, v173
	v_fma_f32 v4, v84, v4, v174
	v_fma_f32 v5, v85, v5, v175
	global_store_dwordx4 v245, v[2:5], s[26:27] offset:192
	s_add_u32 s44, s94, 0x7b48000
	s_addc_u32 s45, s95, 0
	s_waitcnt vmcnt(16)
	v_add_f32_e32 v226, 1.0, v226
	v_add_f32_e32 v227, 1.0, v227
	v_add_f32_e32 v228, 1.0, v228
	v_add_f32_e32 v229, 1.0, v229
	v_add_f32_e32 v230, 1.0, v230
	v_add_f32_e32 v231, 1.0, v231
	v_add_f32_e32 v232, 1.0, v232
	v_add_f32_e32 v233, 1.0, v233
	v_add_f32_e32 v234, 1.0, v234
	v_add_f32_e32 v235, 1.0, v235
	v_add_f32_e32 v236, 1.0, v236
	v_add_f32_e32 v237, 1.0, v237
	v_add_f32_e32 v238, 1.0, v238
	v_add_f32_e32 v239, 1.0, v239
	v_add_f32_e32 v240, 1.0, v240
	v_add_f32_e32 v241, 1.0, v241
	v_lshrrev_b32_e32 v218, 1, v242
	v_lshrrev_b32_e32 v219, 1, v243
	v_lshrrev_b32_e32 v220, 1, v244
	v_lshrrev_b32_e32 v221, 1, v245
	v_fma_f32 v62, v226, v62, v38
	v_fma_f32 v63, v227, v63, v39
	v_fma_f32 v64, v228, v64, v40
	v_fma_f32 v65, v229, v65, v41
	v_cvt_pk_bf16_f32 v62, v62, v63
	v_cvt_pk_bf16_f32 v63, v64, v65
	global_store_dwordx2 v218, v[62:63], s[44:45]
	v_fma_f32 v86, v230, v86, v42
	v_fma_f32 v87, v231, v87, v43
	v_fma_f32 v88, v232, v88, v44
	v_fma_f32 v89, v233, v89, v45
	v_cvt_pk_bf16_f32 v86, v86, v87
	v_cvt_pk_bf16_f32 v87, v88, v89
	global_store_dwordx2 v218, v[86:87], s[44:45] offset:32
	v_fma_f32 v70, v234, v70, v46
	v_fma_f32 v71, v235, v71, v47
	v_fma_f32 v72, v236, v72, v48
	v_fma_f32 v73, v237, v73, v49
	v_cvt_pk_bf16_f32 v70, v70, v71
	v_cvt_pk_bf16_f32 v71, v72, v73
	global_store_dwordx2 v218, v[70:71], s[44:45] offset:64
	v_fma_f32 v176, v238, v176, v50
	v_fma_f32 v177, v239, v177, v51
	v_fma_f32 v178, v240, v178, v52
	v_fma_f32 v179, v241, v179, v53
	v_cvt_pk_bf16_f32 v176, v176, v177
	v_cvt_pk_bf16_f32 v177, v178, v179
	global_store_dwordx2 v218, v[176:177], s[44:45] offset:96
	v_fma_f32 v202, v226, v202, v38
	v_fma_f32 v203, v227, v203, v39
	v_fma_f32 v204, v228, v204, v40
	v_fma_f32 v205, v229, v205, v41
	v_cvt_pk_bf16_f32 v202, v202, v203
	v_cvt_pk_bf16_f32 v203, v204, v205
	global_store_dwordx2 v219, v[202:203], s[44:45]
	v_fma_f32 v54, v230, v54, v42
	v_fma_f32 v55, v231, v55, v43
	v_fma_f32 v56, v232, v56, v44
	v_fma_f32 v57, v233, v57, v45
	v_cvt_pk_bf16_f32 v54, v54, v55
	v_cvt_pk_bf16_f32 v55, v56, v57
	global_store_dwordx2 v219, v[54:55], s[44:45] offset:32
	v_fma_f32 v58, v234, v58, v46
	v_fma_f32 v59, v235, v59, v47
	v_fma_f32 v60, v236, v60, v48
	v_fma_f32 v61, v237, v61, v49
	v_cvt_pk_bf16_f32 v58, v58, v59
	v_cvt_pk_bf16_f32 v59, v60, v61
	global_store_dwordx2 v219, v[58:59], s[44:45] offset:64
	v_fma_f32 v34, v238, v34, v50
	v_fma_f32 v35, v239, v35, v51
	v_fma_f32 v36, v240, v36, v52
	v_fma_f32 v37, v241, v37, v53
	v_cvt_pk_bf16_f32 v34, v34, v35
	v_cvt_pk_bf16_f32 v35, v36, v37
	global_store_dwordx2 v219, v[34:35], s[44:45] offset:96
	v_fma_f32 v30, v226, v30, v38
	v_fma_f32 v31, v227, v31, v39
	v_fma_f32 v32, v228, v32, v40
	v_fma_f32 v33, v229, v33, v41
	v_cvt_pk_bf16_f32 v30, v30, v31
	v_cvt_pk_bf16_f32 v31, v32, v33
	global_store_dwordx2 v220, v[30:31], s[44:45]
	v_fma_f32 v26, v230, v26, v42
	v_fma_f32 v27, v231, v27, v43
	v_fma_f32 v28, v232, v28, v44
	v_fma_f32 v29, v233, v29, v45
	v_cvt_pk_bf16_f32 v26, v26, v27
	v_cvt_pk_bf16_f32 v27, v28, v29
	global_store_dwordx2 v220, v[26:27], s[44:45] offset:32
	v_fma_f32 v22, v234, v22, v46
	v_fma_f32 v23, v235, v23, v47
	v_fma_f32 v24, v236, v24, v48
	v_fma_f32 v25, v237, v25, v49
	v_cvt_pk_bf16_f32 v22, v22, v23
	v_cvt_pk_bf16_f32 v23, v24, v25
	global_store_dwordx2 v220, v[22:23], s[44:45] offset:64
	v_fma_f32 v18, v238, v18, v50
	v_fma_f32 v19, v239, v19, v51
	v_fma_f32 v20, v240, v20, v52
	v_fma_f32 v21, v241, v21, v53
	v_cvt_pk_bf16_f32 v18, v18, v19
	v_cvt_pk_bf16_f32 v19, v20, v21
	global_store_dwordx2 v220, v[18:19], s[44:45] offset:96
	v_fma_f32 v14, v226, v14, v38
	v_fma_f32 v15, v227, v15, v39
	v_fma_f32 v16, v228, v16, v40
	v_fma_f32 v17, v229, v17, v41
	v_cvt_pk_bf16_f32 v14, v14, v15
	v_cvt_pk_bf16_f32 v15, v16, v17
	global_store_dwordx2 v221, v[14:15], s[44:45]
	v_fma_f32 v10, v230, v10, v42
	v_fma_f32 v11, v231, v11, v43
	v_fma_f32 v12, v232, v12, v44
	v_fma_f32 v13, v233, v13, v45
	v_cvt_pk_bf16_f32 v10, v10, v11
	v_cvt_pk_bf16_f32 v11, v12, v13
	global_store_dwordx2 v221, v[10:11], s[44:45] offset:32
	v_fma_f32 v6, v234, v6, v46
	v_fma_f32 v7, v235, v7, v47
	v_fma_f32 v8, v236, v8, v48
	v_fma_f32 v9, v237, v9, v49
	v_cvt_pk_bf16_f32 v6, v6, v7
	v_cvt_pk_bf16_f32 v7, v8, v9
	global_store_dwordx2 v221, v[6:7], s[44:45] offset:64
	v_fma_f32 v2, v238, v2, v50
	v_fma_f32 v3, v239, v3, v51
	v_fma_f32 v4, v240, v4, v52
	v_fma_f32 v5, v241, v5, v53
	v_cvt_pk_bf16_f32 v2, v2, v3
	v_cvt_pk_bf16_f32 v3, v4, v5
	global_store_dwordx2 v221, v[2:3], s[44:45] offset:96
	v_readlane_b32 s78, v255, 33
	v_readlane_b32 s79, v255, 34
	s_barrier
	s_load_dword s6, s[78:79], 0x0
	s_mov_b64 s[76:77], 0x7b4c180
	s_mov_b64 s[68:69], 0x7b54180
	s_mov_b64 s[74:75], 0x68800
	s_waitcnt lgkmcnt(0)
	s_add_i32 s60, s6, s60
	s_cmpk_gt_i32 s60, 0xbf
	s_cbranch_scc0 .LBB0_93

.LBB0_413:
	s_mul_hi_u32 s27, s23, 0xaaaaaaab
	s_lshr_b32 s27, s27, 1
	s_mul_i32 s27, s27, 0x24000
	s_waitcnt lgkmcnt(0)
	v_mfma_f32_16x16x32_bf16 v[66:69], v[22:25], v[26:29], v[66:69]
	v_add_u32_e32 v222, s14, v113
	s_mul_hi_u32 s34, s19, 0xaaaaaaab
	s_lshr_b32 s34, s34, 1
	v_mfma_f32_16x16x32_bf16 v[62:65], v[18:21], v[26:29], v[62:65]
	s_mul_i32 s34, s34, 0x24000
	v_subrev_u32_e32 v182, s34, v126
	v_subrev_u32_e32 v191, s34, v127
	v_mfma_f32_16x16x32_bf16 v[58:61], v[10:13], v[26:29], v[58:61]
	v_subrev_u32_e32 v201, s34, v128
	v_mfma_f32_16x16x32_bf16 v[54:57], v[6:9], v[26:29], v[54:57]
	v_subrev_u32_e32 v26, s27, v125
	v_mfma_f32_16x16x32_bf16 v[50:53], v[22:25], v[14:17], v[50:53]
	v_mfma_f32_16x16x32_bf16 v[46:49], v[18:21], v[14:17], v[46:49]
	v_mfma_f32_16x16x32_bf16 v[42:45], v[10:13], v[14:17], v[42:45]
	v_mfma_f32_16x16x32_bf16 v[38:41], v[6:9], v[14:17], v[38:41]
	v_subrev_u32_e32 v14, s27, v129
	v_add_u32_e32 v16, v222, v26
	v_add_u32_e32 v14, v222, v14
	v_mfma_f32_16x16x32_bf16 v[34:37], v[22:25], v[30:33], v[34:37]
	v_subrev_u32_e32 v15, s34, v130
	v_mfma_f32_16x16x32_bf16 v[86:89], v[22:25], v[2:5], v[86:89]
	ds_read_b128 v[22:25], v16
	ds_read_b128 v[174:177], v16 offset:2048
	ds_read_b128 v[178:181], v16 offset:4096
	ds_read_b128 v[202:205], v16 offset:6144
	ds_read_b128 v[206:209], v14 offset:32768
	ds_read_b128 v[210:213], v14 offset:34816
	ds_read_b128 v[214:217], v14 offset:36864
	ds_read_b128 v[218:221], v14 offset:38912
	v_mfma_f32_16x16x32_bf16 v[74:77], v[18:21], v[30:33], v[74:77]
	v_mfma_f32_16x16x32_bf16 v[70:73], v[10:13], v[30:33], v[70:73]
	v_mfma_f32_16x16x32_bf16 v[78:81], v[6:9], v[30:33], v[78:81]
	v_mfma_f32_16x16x32_bf16 v[94:97], v[18:21], v[2:5], v[94:97]
	v_mfma_f32_16x16x32_bf16 v[90:93], v[10:13], v[2:5], v[90:93]
	v_mfma_f32_16x16x32_bf16 v[82:85], v[6:9], v[2:5], v[82:85]
	s_add_i32 s27, s13, 4
	s_mul_i32 s34, s27, 0xab
	s_bfe_u32 s34, s34, 0x70009
	s_mul_i32 s34, s34, 3
	s_sub_i32 s27, s27, s34
	s_and_b32 s27, s27, 0xff
	s_mul_i32 s27, s27, 0xc000
	s_waitcnt vmcnt(6)
	v_add_u32_e32 v2, v222, v15
	v_add_u32_e32 v6, v222, v201
	s_waitcnt lgkmcnt(0)
	v_mfma_f32_16x16x32_bf16 v[66:69], v[206:209], v[174:177], v[66:69]
	s_mov_b64 s[36:37], 0xe1d8180
	s_add_i32 s34, s27, s8
	s_waitcnt lgkmcnt(0)
	v_mfma_f32_16x16x32_bf16 v[62:65], v[210:213], v[174:177], v[62:65]
	s_barrier
	ds_read_b128 v[30:33], v2
	ds_read_b128 v[26:29], v2 offset:2048
	ds_read_b128 v[14:17], v2 offset:4096
	ds_read_b128 v[2:5], v2 offset:6144
	v_mfma_f32_16x16x32_bf16 v[58:61], v[214:217], v[174:177], v[58:61]
	v_add_u32_e32 v7, v222, v191
	s_mov_b32 m0, s34
	s_add_i32 s27, s27, s9
	v_mfma_f32_16x16x32_bf16 v[54:57], v[218:221], v[174:177], v[54:57]
	v_lshl_add_u64 v[174:175], v[108:109], 0, v[98:99]
	v_lshl_add_u64 v[176:177], v[174:175], 0, s[36:37]
	s_mov_b64 s[36:37], 0xe1e8180
	v_mfma_f32_16x16x32_bf16 v[34:37], v[206:209], v[22:25], v[34:37]
	s_add_i32 s23, s23, 1
	v_mfma_f32_16x16x32_bf16 v[74:77], v[210:213], v[22:25], v[74:77]
	v_mfma_f32_16x16x32_bf16 v[70:73], v[214:217], v[22:25], v[70:73]
	v_mfma_f32_16x16x32_bf16 v[78:81], v[218:221], v[22:25], v[78:81]
	ds_read_b128 v[22:25], v6
	ds_read_b128 v[18:21], v7
	v_add_u32_e32 v6, v222, v182
	ds_read_b128 v[10:13], v6
	ds_read_b128 v[6:9], v6 offset:2048
	global_load_lds_dwordx4 v[176:177], off
	v_lshl_add_u64 v[176:177], v[174:175], 0, s[36:37]
	s_add_i32 m0, s34, 0x400
	s_mov_b64 s[36:37], 0xe1f8180
	global_load_lds_dwordx4 v[176:177], off
	v_lshl_add_u64 v[176:177], v[174:175], 0, s[36:37]
	s_add_i32 m0, s34, 0x800
	s_mov_b64 s[36:37], 0xe208180
	global_load_lds_dwordx4 v[176:177], off
	v_lshl_add_u64 v[174:175], v[174:175], 0, s[36:37]
	s_add_i32 m0, s34, 0xc00
	s_mov_b64 s[36:37], 0x4300180
	global_load_lds_dwordx4 v[174:175], off
	v_lshl_add_u64 v[174:175], v[110:111], 0, v[98:99]
	v_lshl_add_u64 v[176:177], v[174:175], 0, s[36:37]
	s_add_i32 m0, s27, 0x8000
	s_mov_b64 s[36:37], 0x4310180
	global_load_lds_dwordx4 v[176:177], off
	v_lshl_add_u64 v[174:175], v[174:175], 0, s[36:37]
	s_add_i32 m0, s27, 0x8400
	v_mfma_f32_16x16x32_bf16 v[50:53], v[206:209], v[178:181], v[50:53]
	global_load_lds_dwordx4 v[174:175], off
	v_mfma_f32_16x16x32_bf16 v[46:49], v[210:213], v[178:181], v[46:49]
	v_mfma_f32_16x16x32_bf16 v[42:45], v[214:217], v[178:181], v[42:45]
	v_mfma_f32_16x16x32_bf16 v[38:41], v[218:221], v[178:181], v[38:41]
	v_mfma_f32_16x16x32_bf16 v[86:89], v[206:209], v[202:205], v[86:89]
	v_mfma_f32_16x16x32_bf16 v[94:97], v[210:213], v[202:205], v[94:97]
	v_mfma_f32_16x16x32_bf16 v[90:93], v[214:217], v[202:205], v[90:93]
	v_mfma_f32_16x16x32_bf16 v[82:85], v[218:221], v[202:205], v[82:85]
	s_add_i32 s13, s13, 1
	s_add_i32 s14, s14, 0xc000
	s_add_i32 s19, s19, 1
	v_lshl_add_u64 v[108:109], v[108:109], 0, s[2:3]
	s_cmp_eq_u32 s14, 0x2dc000
	v_lshl_add_u64 v[110:111], v[110:111], 0, s[2:3]
	s_cbranch_scc0 .LBB0_413
	s_waitcnt lgkmcnt(0)
	v_mfma_f32_16x16x32_bf16 v[34:37], v[22:25], v[30:33], v[34:37]
	v_mfma_f32_16x16x32_bf16 v[74:77], v[18:21], v[30:33], v[74:77]
	v_mfma_f32_16x16x32_bf16 v[70:73], v[10:13], v[30:33], v[70:73]
	v_mfma_f32_16x16x32_bf16 v[30:33], v[6:9], v[30:33], v[78:81]
	v_mfma_f32_16x16x32_bf16 v[66:69], v[22:25], v[26:29], v[66:69]
	v_mfma_f32_16x16x32_bf16 v[62:65], v[18:21], v[26:29], v[62:65]
	v_mfma_f32_16x16x32_bf16 v[58:61], v[10:13], v[26:29], v[58:61]
	v_mfma_f32_16x16x32_bf16 v[26:29], v[6:9], v[26:29], v[54:57]
	v_mfma_f32_16x16x32_bf16 v[50:53], v[22:25], v[14:17], v[50:53]
	v_mfma_f32_16x16x32_bf16 v[46:49], v[18:21], v[14:17], v[46:49]
	v_mfma_f32_16x16x32_bf16 v[42:45], v[10:13], v[14:17], v[42:45]
	v_mfma_f32_16x16x32_bf16 v[14:17], v[6:9], v[14:17], v[38:41]
	v_mfma_f32_16x16x32_bf16 v[22:25], v[22:25], v[2:5], v[86:89]
	s_nop 1
	ds_read_b128 v[38:41], v131
	ds_read_b128 v[54:57], v132 offset:2048
	ds_read_b128 v[78:81], v132 offset:4096
	ds_read_b128 v[86:89], v132 offset:6144
	v_mfma_f32_16x16x32_bf16 v[18:21], v[18:21], v[2:5], v[94:97]
	v_mfma_f32_16x16x32_bf16 v[10:13], v[10:13], v[2:5], v[90:93]
	s_nop 2
	ds_read_b128 v[90:93], v133 offset:32768
	ds_read_b128 v[94:97], v134 offset:34816
	ds_read_b128 v[108:111], v134 offset:36864
	ds_read_b128 v[174:177], v134 offset:38912
	v_mfma_f32_16x16x32_bf16 v[2:5], v[6:9], v[2:5], v[82:85]
	s_waitcnt lgkmcnt(0)
	v_mfma_f32_16x16x32_bf16 v[6:9], v[90:93], v[38:41], v[34:37]
	s_waitcnt vmcnt(6)
	s_waitcnt lgkmcnt(0)
	s_barrier
	v_mfma_f32_16x16x32_bf16 v[34:37], v[94:97], v[38:41], v[74:77]
	v_mfma_f32_16x16x32_bf16 v[70:73], v[108:111], v[38:41], v[70:73]
	v_mfma_f32_16x16x32_bf16 v[30:33], v[174:177], v[38:41], v[30:33]
	v_mfma_f32_16x16x32_bf16 v[38:41], v[90:93], v[54:57], v[66:69]
	v_mfma_f32_16x16x32_bf16 v[62:65], v[94:97], v[54:57], v[62:65]
	v_mfma_f32_16x16x32_bf16 v[58:61], v[108:111], v[54:57], v[58:61]
	v_mfma_f32_16x16x32_bf16 v[26:29], v[174:177], v[54:57], v[26:29]
	v_add_u32_e32 v54, v124, v115
	ds_read_b128 v[54:57], v54
	ds_read_b128 v[66:69], v135 offset:2048
	v_mfma_f32_16x16x32_bf16 v[50:53], v[90:93], v[78:81], v[50:53]
	v_mfma_f32_16x16x32_bf16 v[46:49], v[94:97], v[78:81], v[46:49]
	v_mfma_f32_16x16x32_bf16 v[42:45], v[108:111], v[78:81], v[42:45]
	v_mfma_f32_16x16x32_bf16 v[22:25], v[90:93], v[86:89], v[22:25]
	v_add_u32_e32 v90, 0x20800, v164
	v_mfma_f32_16x16x32_bf16 v[18:21], v[94:97], v[86:89], v[18:21]
	v_add_u32_e32 v94, 0x21000, v164
	v_mfma_f32_16x16x32_bf16 v[10:13], v[108:111], v[86:89], v[10:13]
	v_add_u32_e32 v108, 0x21800, v164
	v_mfma_f32_16x16x32_bf16 v[14:17], v[174:177], v[78:81], v[14:17]
	ds_read_b128 v[74:77], v135 offset:4096
	ds_read_b128 v[78:81], v135 offset:6144
	ds_read_b128 v[82:85], v163
	ds_read_b128 v[90:93], v90
	ds_read_b128 v[94:97], v94
	ds_read_b128 v[108:111], v108
	v_mfma_f32_16x16x32_bf16 v[2:5], v[174:177], v[86:89], v[2:5]
	s_waitcnt lgkmcnt(0)
	v_mfma_f32_16x16x32_bf16 v[6:9], v[82:85], v[54:57], v[6:9]
	v_mfma_f32_16x16x32_bf16 v[34:37], v[90:93], v[54:57], v[34:37]
	v_mfma_f32_16x16x32_bf16 v[70:73], v[94:97], v[54:57], v[70:73]
	v_mfma_f32_16x16x32_bf16 v[30:33], v[108:111], v[54:57], v[30:33]
	v_mfma_f32_16x16x32_bf16 v[54:57], v[90:93], v[66:69], v[62:65]
	s_nop 2
	v_add_u32_e32 v62, v124, v119
	v_mfma_f32_16x16x32_bf16 v[38:41], v[82:85], v[66:69], v[38:41]
	v_mfma_f32_16x16x32_bf16 v[58:61], v[94:97], v[66:69], v[58:61]
	v_mfma_f32_16x16x32_bf16 v[26:29], v[108:111], v[66:69], v[26:29]
	v_mfma_f32_16x16x32_bf16 v[50:53], v[82:85], v[74:77], v[50:53]
	v_mfma_f32_16x16x32_bf16 v[46:49], v[90:93], v[74:77], v[46:49]
	v_mfma_f32_16x16x32_bf16 v[42:45], v[94:97], v[74:77], v[42:45]
	v_mfma_f32_16x16x32_bf16 v[14:17], v[108:111], v[74:77], v[14:17]
	v_mfma_f32_16x16x32_bf16 v[22:25], v[82:85], v[78:81], v[22:25]
	ds_read_b128 v[62:65], v62
	ds_read_b128 v[66:69], v165
	ds_read_b128 v[74:77], v166
	ds_read_b128 v[82:85], v167
	v_mfma_f32_16x16x32_bf16 v[18:21], v[90:93], v[78:81], v[18:21]
	v_mfma_f32_16x16x32_bf16 v[10:13], v[94:97], v[78:81], v[10:13]
	ds_read_b128 v[86:89], v168
	ds_read_b128 v[90:93], v169
	ds_read_b128 v[94:97], v170
	ds_read_b128 v[174:177], v171
	v_mfma_f32_16x16x32_bf16 v[2:5], v[108:111], v[78:81], v[2:5]
	s_waitcnt vmcnt(0)
	s_waitcnt lgkmcnt(0)
	v_mfma_f32_16x16x32_bf16 v[6:9], v[86:89], v[62:65], v[6:9]
	s_waitcnt lgkmcnt(0)
	s_barrier
	v_mfma_f32_16x16x32_bf16 v[34:37], v[90:93], v[62:65], v[34:37]
	v_mfma_f32_16x16x32_bf16 v[70:73], v[94:97], v[62:65], v[70:73]
	v_mfma_f32_16x16x32_bf16 v[30:33], v[174:177], v[62:65], v[30:33]
	v_mfma_f32_16x16x32_bf16 v[38:41], v[86:89], v[66:69], v[38:41]
	v_mfma_f32_16x16x32_bf16 v[54:57], v[90:93], v[66:69], v[54:57]
	v_mfma_f32_16x16x32_bf16 v[58:61], v[94:97], v[66:69], v[58:61]
	v_mfma_f32_16x16x32_bf16 v[26:29], v[174:177], v[66:69], v[26:29]
	v_mfma_f32_16x16x32_bf16 v[50:53], v[86:89], v[74:77], v[50:53]
	v_mfma_f32_16x16x32_bf16 v[46:49], v[90:93], v[74:77], v[46:49]
	v_mfma_f32_16x16x32_bf16 v[42:45], v[94:97], v[74:77], v[42:45]
	v_mfma_f32_16x16x32_bf16 v[14:17], v[174:177], v[74:77], v[14:17]
	ds_read_b128 v[62:65], v164 offset:38912
	ds_read_b128 v[66:69], v164 offset:36864
	ds_read_b128 v[74:77], v164 offset:34816
	ds_read_b128 v[78:81], v161 offset:32768
	v_mfma_f32_16x16x32_bf16 v[22:25], v[86:89], v[82:85], v[22:25]
	v_mfma_f32_16x16x32_bf16 v[18:21], v[90:93], v[82:85], v[18:21]
	v_mfma_f32_16x16x32_bf16 v[10:13], v[94:97], v[82:85], v[10:13]
	ds_read_b128 v[86:89], v173 offset:6144
	ds_read_b128 v[90:93], v173 offset:4096
	ds_read_b128 v[94:97], v173 offset:2048
	ds_read_b128 v[108:111], v172
	v_mfma_f32_16x16x32_bf16 v[2:5], v[174:177], v[82:85], v[2:5]
	s_waitcnt lgkmcnt(0)
	v_mfma_f32_16x16x32_bf16 v[38:41], v[78:81], v[94:97], v[38:41]
	v_add_u32_e32 v82, v114, v119
	v_add_u32_e32 v172, v118, v119
	v_mfma_f32_16x16x32_bf16 v[54:57], v[74:77], v[94:97], v[54:57]
	v_mfma_f32_16x16x32_bf16 v[58:61], v[66:69], v[94:97], v[58:61]
	v_mfma_f32_16x16x32_bf16 v[26:29], v[62:65], v[94:97], v[26:29]
	v_add_u32_e32 v94, v117, v119
	v_mfma_f32_16x16x32_bf16 v[50:53], v[78:81], v[90:93], v[50:53]
	v_mfma_f32_16x16x32_bf16 v[46:49], v[74:77], v[90:93], v[46:49]
	v_mfma_f32_16x16x32_bf16 v[42:45], v[66:69], v[90:93], v[42:45]
	v_mfma_f32_16x16x32_bf16 v[14:17], v[62:65], v[90:93], v[14:17]
	v_add_u32_e32 v90, v116, v119
	v_mfma_f32_16x16x32_bf16 v[6:9], v[78:81], v[108:111], v[6:9]
	v_mfma_f32_16x16x32_bf16 v[34:37], v[74:77], v[108:111], v[34:37]
	v_mfma_f32_16x16x32_bf16 v[70:73], v[66:69], v[108:111], v[70:73]
	v_mfma_f32_16x16x32_bf16 v[30:33], v[62:65], v[108:111], v[30:33]
	v_mfma_f32_16x16x32_bf16 v[78:81], v[78:81], v[86:89], v[22:25]
	s_nop 2
	ds_read_b128 v[22:25], v82
	ds_read_b128 v[82:85], v90 offset:2048
	v_mfma_f32_16x16x32_bf16 v[74:77], v[74:77], v[86:89], v[18:21]
	s_nop 2
	ds_read_b128 v[18:21], v90 offset:4096
	ds_read_b128 v[90:93], v90 offset:6144
	v_mfma_f32_16x16x32_bf16 v[66:69], v[66:69], v[86:89], v[10:13]
	s_nop 2
	ds_read_b128 v[10:13], v94 offset:32768
	ds_read_b128 v[94:97], v172 offset:34816
	ds_read_b128 v[108:111], v172 offset:36864
	ds_read_b128 v[172:175], v172 offset:38912
	v_mfma_f32_16x16x32_bf16 v[2:5], v[62:65], v[86:89], v[2:5]
	s_waitcnt vmcnt(0)
	s_waitcnt lgkmcnt(0)
	v_mfma_f32_16x16x32_bf16 v[2:5], v[172:175], v[90:93], v[2:5]
	s_waitcnt lgkmcnt(0)
	s_barrier
	v_mfma_f32_16x16x32_bf16 v[62:65], v[10:13], v[22:25], v[6:9]
	v_mfma_f32_16x16x32_bf16 v[86:89], v[94:97], v[22:25], v[34:37]
	v_mfma_f32_16x16x32_bf16 v[70:73], v[108:111], v[22:25], v[70:73]
	v_mfma_f32_16x16x32_bf16 v[176:179], v[172:175], v[22:25], v[30:33]
	v_mfma_f32_16x16x32_bf16 v[202:205], v[10:13], v[82:85], v[38:41]
	v_mfma_f32_16x16x32_bf16 v[54:57], v[94:97], v[82:85], v[54:57]
	v_mfma_f32_16x16x32_bf16 v[58:61], v[108:111], v[82:85], v[58:61]
	v_mfma_f32_16x16x32_bf16 v[34:37], v[172:175], v[82:85], v[26:29]
	v_mfma_f32_16x16x32_bf16 v[30:33], v[10:13], v[18:21], v[50:53]
	v_mfma_f32_16x16x32_bf16 v[26:29], v[94:97], v[18:21], v[46:49]
	v_mfma_f32_16x16x32_bf16 v[22:25], v[108:111], v[18:21], v[42:45]
	v_mfma_f32_16x16x32_bf16 v[18:21], v[172:175], v[18:21], v[14:17]
	v_mfma_f32_16x16x32_bf16 v[14:17], v[10:13], v[90:93], v[78:81]
	v_mfma_f32_16x16x32_bf16 v[10:13], v[94:97], v[90:93], v[74:77]
	v_mfma_f32_16x16x32_bf16 v[6:9], v[108:111], v[90:93], v[66:69]
	s_mul_hi_i32 s54, s70, 0x2aaaaaab
	s_lshr_b32 s55, s54, 31
	s_ashr_i32 s54, s54, 2
	s_add_i32 s13, s54, s55
	s_mul_i32 s54, s13, 24
	s_sub_i32 s14, s70, s54
	v_readfirstlane_b32 s54, v137
	s_lshr_b32 s54, s54, 6
	s_and_b32 s19, s54, 1
	s_lshr_b32 s54, s54, 1
	s_lshl_b32 s54, s54, 6
	s_lshl_b32 s50, s14, 8
	s_add_i32 s50, s50, s54
	s_lshl_b32 s51, s13, 7
	s_lshl_b32 s54, s19, 6
	s_add_i32 s51, s51, s54
	s_add_i32 s54, s50, 0xfffff000
	s_ashr_i32 s54, s54, 10
	s_add_i32 s54, s54, 1
	s_cmpk_lt_i32 s50, 0x1000
	s_cselect_b32 s52, 0, s54
	v_readlane_b32 s53, v255, 40
	v_and_b32_e32 v250, 63, v137
	v_and_b32_e32 v251, 15, v250
	v_lshrrev_b32_e32 v252, 4, v250
	s_mul_i32 s54, s53, 3
	s_add_i32 s54, s54, s52
	s_mul_i32 s54, s54, 0x6000
	s_add_u32 s22, s94, 0x6300000
	s_addc_u32 s23, s95, 0
	s_add_u32 s22, s22, s54
	s_addc_u32 s23, s23, 0
	s_add_u32 s26, s94, 0x6348000
	s_addc_u32 s27, s95, 0
	v_add_u32_e32 v242, s50, v251
	v_lshlrev_b32_e32 v242, 12, v242
	s_lshl_b32 s54, s51, 2
	v_lshl_add_u32 v242, v252, 4, v242
	v_add_u32_e32 v242, s54, v242
	s_add_i32 s55, s51, 5120
	s_lshl_b32 s55, s55, 2
	v_lshl_add_u32 v246, v252, 4, s55
	v_add_u32_e32 v243, 0x10000, v242
	v_add_u32_e32 v244, 0x20000, v242
	v_add_u32_e32 v245, 0x30000, v242
	global_load_dwordx4 v[226:229], v246, s[22:23]
	global_load_dwordx4 v[230:233], v246, s[22:23] offset:64
	global_load_dwordx4 v[234:237], v246, s[22:23] offset:128
	global_load_dwordx4 v[238:241], v246, s[22:23] offset:192
	global_load_dwordx4 v[38:41], v242, s[26:27]
	global_load_dwordx4 v[42:45], v242, s[26:27] offset:64
	global_load_dwordx4 v[46:49], v242, s[26:27] offset:128
	global_load_dwordx4 v[50:53], v242, s[26:27] offset:192
	global_load_dwordx4 v[66:69], v243, s[26:27]
	global_load_dwordx4 v[74:77], v243, s[26:27] offset:64
	global_load_dwordx4 v[78:81], v243, s[26:27] offset:128
	global_load_dwordx4 v[82:85], v243, s[26:27] offset:192
	global_load_dwordx4 v[90:93], v244, s[26:27]
	global_load_dwordx4 v[94:97], v244, s[26:27] offset:64
	global_load_dwordx4 v[108:111], v244, s[26:27] offset:128
	global_load_dwordx4 v[172:175], v244, s[26:27] offset:192
	global_load_dwordx4 v[206:209], v245, s[26:27]
	global_load_dwordx4 v[210:213], v245, s[26:27] offset:64
	global_load_dwordx4 v[214:217], v245, s[26:27] offset:128
	global_load_dwordx4 v[218:221], v245, s[26:27] offset:192
	v_mov_b32_e32 v248, 0x3fd744fd
	v_mov_b32_e32 v249, 0x3fd744fd
	s_waitcnt vmcnt(12)
	v_pk_mul_f32 v[38:39], v[38:39], v[248:249]
	v_pk_mul_f32 v[40:41], v[40:41], v[248:249]
	v_pk_fma_f32 v[62:63], v[62:63], v[226:227], v[38:39]
	v_pk_fma_f32 v[64:65], v[64:65], v[228:229], v[40:41]
	v_pk_mul_f32 v[42:43], v[42:43], v[248:249]
	v_pk_mul_f32 v[44:45], v[44:45], v[248:249]
	v_pk_fma_f32 v[86:87], v[86:87], v[230:231], v[42:43]
	v_pk_fma_f32 v[88:89], v[88:89], v[232:233], v[44:45]
	v_pk_mul_f32 v[46:47], v[46:47], v[248:249]
	v_pk_mul_f32 v[48:49], v[48:49], v[248:249]
	v_pk_fma_f32 v[70:71], v[70:71], v[234:235], v[46:47]
	v_pk_fma_f32 v[72:73], v[72:73], v[236:237], v[48:49]
	v_pk_mul_f32 v[50:51], v[50:51], v[248:249]
	v_pk_mul_f32 v[52:53], v[52:53], v[248:249]
	v_pk_fma_f32 v[176:177], v[176:177], v[238:239], v[50:51]
	v_pk_fma_f32 v[178:179], v[178:179], v[240:241], v[52:53]
	s_waitcnt vmcnt(8)
	v_pk_mul_f32 v[66:67], v[66:67], v[248:249]
	v_pk_mul_f32 v[68:69], v[68:69], v[248:249]
	v_pk_fma_f32 v[202:203], v[202:203], v[226:227], v[66:67]
	v_pk_fma_f32 v[204:205], v[204:205], v[228:229], v[68:69]
	v_pk_mul_f32 v[74:75], v[74:75], v[248:249]
	v_pk_mul_f32 v[76:77], v[76:77], v[248:249]
	v_pk_fma_f32 v[54:55], v[54:55], v[230:231], v[74:75]
	v_pk_fma_f32 v[56:57], v[56:57], v[232:233], v[76:77]
	v_pk_mul_f32 v[78:79], v[78:79], v[248:249]
	v_pk_mul_f32 v[80:81], v[80:81], v[248:249]
	v_pk_fma_f32 v[58:59], v[58:59], v[234:235], v[78:79]
	v_pk_fma_f32 v[60:61], v[60:61], v[236:237], v[80:81]
	v_pk_mul_f32 v[82:83], v[82:83], v[248:249]
	v_pk_mul_f32 v[84:85], v[84:85], v[248:249]
	v_pk_fma_f32 v[34:35], v[34:35], v[238:239], v[82:83]
	v_pk_fma_f32 v[36:37], v[36:37], v[240:241], v[84:85]
	s_waitcnt vmcnt(4)
	v_pk_mul_f32 v[90:91], v[90:91], v[248:249]
	v_pk_mul_f32 v[92:93], v[92:93], v[248:249]
	v_pk_fma_f32 v[30:31], v[30:31], v[226:227], v[90:91]
	v_pk_fma_f32 v[32:33], v[32:33], v[228:229], v[92:93]
	v_pk_mul_f32 v[94:95], v[94:95], v[248:249]
	v_pk_mul_f32 v[96:97], v[96:97], v[248:249]
	v_pk_fma_f32 v[26:27], v[26:27], v[230:231], v[94:95]
	v_pk_fma_f32 v[28:29], v[28:29], v[232:233], v[96:97]
	v_pk_mul_f32 v[108:109], v[108:109], v[248:249]
	v_pk_mul_f32 v[110:111], v[110:111], v[248:249]
	v_pk_fma_f32 v[22:23], v[22:23], v[234:235], v[108:109]
	v_pk_fma_f32 v[24:25], v[24:25], v[236:237], v[110:111]
	v_pk_mul_f32 v[172:173], v[172:173], v[248:249]
	v_pk_mul_f32 v[174:175], v[174:175], v[248:249]
	v_pk_fma_f32 v[18:19], v[18:19], v[238:239], v[172:173]
	v_pk_fma_f32 v[20:21], v[20:21], v[240:241], v[174:175]
	s_waitcnt vmcnt(0)
	v_pk_mul_f32 v[206:207], v[206:207], v[248:249]
	v_pk_mul_f32 v[208:209], v[208:209], v[248:249]
	v_pk_fma_f32 v[14:15], v[14:15], v[226:227], v[206:207]
	v_pk_fma_f32 v[16:17], v[16:17], v[228:229], v[208:209]
	v_pk_mul_f32 v[210:211], v[210:211], v[248:249]
	v_pk_mul_f32 v[212:213], v[212:213], v[248:249]
	v_pk_fma_f32 v[10:11], v[10:11], v[230:231], v[210:211]
	v_pk_fma_f32 v[12:13], v[12:13], v[232:233], v[212:213]
	v_pk_mul_f32 v[214:215], v[214:215], v[248:249]
	v_pk_mul_f32 v[216:217], v[216:217], v[248:249]
	v_pk_fma_f32 v[6:7], v[6:7], v[234:235], v[214:215]
	v_pk_fma_f32 v[8:9], v[8:9], v[236:237], v[216:217]
	v_pk_mul_f32 v[218:219], v[218:219], v[248:249]
	v_pk_mul_f32 v[220:221], v[220:221], v[248:249]
	v_pk_fma_f32 v[2:3], v[2:3], v[238:239], v[218:219]
	v_pk_fma_f32 v[4:5], v[4:5], v[240:241], v[220:221]
	v_pk_mul_f32 v[208:209], v[62:63], v[62:63]
	v_pk_add_f32 v[206:207], v[62:63], v[64:65]
	v_pk_fma_f32 v[208:209], v[64:65], v[64:65], v[208:209]
	v_pk_add_f32 v[206:207], v[206:207], v[86:87]
	v_pk_fma_f32 v[208:209], v[86:87], v[86:87], v[208:209]
	v_pk_add_f32 v[206:207], v[206:207], v[88:89]
	v_pk_fma_f32 v[208:209], v[88:89], v[88:89], v[208:209]
	v_pk_add_f32 v[206:207], v[206:207], v[70:71]
	v_pk_fma_f32 v[208:209], v[70:71], v[70:71], v[208:209]
	v_pk_add_f32 v[206:207], v[206:207], v[72:73]
	v_pk_fma_f32 v[208:209], v[72:73], v[72:73], v[208:209]
	v_pk_add_f32 v[206:207], v[206:207], v[176:177]
	v_pk_fma_f32 v[208:209], v[176:177], v[176:177], v[208:209]
	v_pk_add_f32 v[206:207], v[206:207], v[178:179]
	v_pk_fma_f32 v[208:209], v[178:179], v[178:179], v[208:209]
	v_add_f32_e32 v206, v206, v207
	v_add_f32_e32 v208, v208, v209
	v_pk_mul_f32 v[212:213], v[202:203], v[202:203]
	v_pk_add_f32 v[210:211], v[202:203], v[204:205]
	v_pk_fma_f32 v[212:213], v[204:205], v[204:205], v[212:213]
	v_pk_add_f32 v[210:211], v[210:211], v[54:55]
	v_pk_fma_f32 v[212:213], v[54:55], v[54:55], v[212:213]
	v_pk_add_f32 v[210:211], v[210:211], v[56:57]
	v_pk_fma_f32 v[212:213], v[56:57], v[56:57], v[212:213]
	v_pk_add_f32 v[210:211], v[210:211], v[58:59]
	v_pk_fma_f32 v[212:213], v[58:59], v[58:59], v[212:213]
	v_pk_add_f32 v[210:211], v[210:211], v[60:61]
	v_pk_fma_f32 v[212:213], v[60:61], v[60:61], v[212:213]
	v_pk_add_f32 v[210:211], v[210:211], v[34:35]
	v_pk_fma_f32 v[212:213], v[34:35], v[34:35], v[212:213]
	v_pk_add_f32 v[210:211], v[210:211], v[36:37]
	v_pk_fma_f32 v[212:213], v[36:37], v[36:37], v[212:213]
	v_add_f32_e32 v210, v210, v211
	v_add_f32_e32 v212, v212, v213
	v_pk_mul_f32 v[216:217], v[30:31], v[30:31]
	v_pk_add_f32 v[214:215], v[30:31], v[32:33]
	v_pk_fma_f32 v[216:217], v[32:33], v[32:33], v[216:217]
	v_pk_add_f32 v[214:215], v[214:215], v[26:27]
	v_pk_fma_f32 v[216:217], v[26:27], v[26:27], v[216:217]
	v_pk_add_f32 v[214:215], v[214:215], v[28:29]
	v_pk_fma_f32 v[216:217], v[28:29], v[28:29], v[216:217]
	v_pk_add_f32 v[214:215], v[214:215], v[22:23]
	v_pk_fma_f32 v[216:217], v[22:23], v[22:23], v[216:217]
	v_pk_add_f32 v[214:215], v[214:215], v[24:25]
	v_pk_fma_f32 v[216:217], v[24:25], v[24:25], v[216:217]
	v_pk_add_f32 v[214:215], v[214:215], v[18:19]
	v_pk_fma_f32 v[216:217], v[18:19], v[18:19], v[216:217]
	v_pk_add_f32 v[214:215], v[214:215], v[20:21]
	v_pk_fma_f32 v[216:217], v[20:21], v[20:21], v[216:217]
	v_add_f32_e32 v214, v214, v215
	v_add_f32_e32 v216, v216, v217
	v_pk_mul_f32 v[220:221], v[14:15], v[14:15]
	v_pk_add_f32 v[218:219], v[14:15], v[16:17]
	v_pk_fma_f32 v[220:221], v[16:17], v[16:17], v[220:221]
	v_pk_add_f32 v[218:219], v[218:219], v[10:11]
	v_pk_fma_f32 v[220:221], v[10:11], v[10:11], v[220:221]
	v_pk_add_f32 v[218:219], v[218:219], v[12:13]
	v_pk_fma_f32 v[220:221], v[12:13], v[12:13], v[220:221]
	v_pk_add_f32 v[218:219], v[218:219], v[6:7]
	v_pk_fma_f32 v[220:221], v[6:7], v[6:7], v[220:221]
	v_pk_add_f32 v[218:219], v[218:219], v[8:9]
	v_pk_fma_f32 v[220:221], v[8:9], v[8:9], v[220:221]
	v_pk_add_f32 v[218:219], v[218:219], v[2:3]
	v_pk_fma_f32 v[220:221], v[2:3], v[2:3], v[220:221]
	v_pk_add_f32 v[218:219], v[218:219], v[4:5]
	v_pk_fma_f32 v[220:221], v[4:5], v[4:5], v[220:221]
	v_add_f32_e32 v218, v218, v219
	v_add_f32_e32 v220, v220, v221
	s_nop 1
	v_permlane16_swap_b32_e32 v206, v210
	v_permlane16_swap_b32_e32 v214, v218
	v_permlane16_swap_b32_e32 v208, v212
	v_permlane16_swap_b32_e32 v216, v220
	v_add_f32_e32 v206, v206, v210
	v_add_f32_e32 v214, v214, v218
	v_add_f32_e32 v208, v208, v212
	v_add_f32_e32 v216, v216, v220
	s_nop 1
	v_permlane32_swap_b32_e32 v206, v214
	v_permlane32_swap_b32_e32 v208, v216
	v_add_f32_e32 v248, v206, v214
	v_add_f32_e32 v249, v208, v216
	s_lshl_b32 s54, s53, 1
	s_add_i32 s54, s54, 0x5a5a5a01
	v_mov_b32_e32 v218, v248
	v_mov_b32_e32 v219, s54
	v_mov_b32_e32 v220, v249
	v_mov_b32_e32 v221, s54
	v_mov_b32_e32 v249, s54
	s_add_u32 s34, s94, 0xc9d8000
	s_addc_u32 s35, s95, 0
	v_add_u32_e32 v247, s50, v250
	v_lshlrev_b32_e32 v247, 4, v247
	s_lshl_b32 s55, s13, 1
	s_add_i32 s55, s55, s19
	s_mul_i32 s55, s55, 0x18000
	v_add_u32_e32 v246, s55, v247
	global_store_dwordx4 v246, v[218:221], s[34:35] sc1
	v_readlane_b32 s36, v253, 15
	v_readlane_b32 s37, v253, 16
	v_readlane_b32 s48, v253, 17
	v_readlane_b32 s49, v253, 18
	s_lshl_b32 s54, s53, 10
	s_add_i32 s54, s54, s51
	s_lshl_b32 s54, s54, 2
	v_lshl_add_u32 v222, v252, 4, s54
	s_nop 3
	global_load_dwordx4 v[66:69], v222, s[36:37]
	global_load_dwordx4 v[74:77], v222, s[36:37] offset:64
	global_load_dwordx4 v[78:81], v222, s[36:37] offset:128
	global_load_dwordx4 v[82:85], v222, s[36:37] offset:192
	global_load_dwordx4 v[90:93], v222, s[48:49]
	global_load_dwordx4 v[94:97], v222, s[48:49] offset:64
	global_load_dwordx4 v[108:111], v222, s[48:49] offset:128
	global_load_dwordx4 v[172:175], v222, s[48:49] offset:192
	s_add_u32 s22, s22, 0x12000
	s_addc_u32 s23, s23, 0
	s_add_i32 s54, s51, 0
	s_lshl_b32 s54, s54, 2
	v_lshl_add_u32 v222, v252, 4, s54
	v_add_u32_e32 v246, 0x1000, v222
	s_cmp_eq_u32 s53, 3
	s_cbranch_scc1 .Lln2_nosh
	global_load_dwordx4 v[38:41], v222, s[22:23]
	global_load_dwordx4 v[42:45], v222, s[22:23] offset:64
	global_load_dwordx4 v[46:49], v222, s[22:23] offset:128
	global_load_dwordx4 v[50:53], v222, s[22:23] offset:192
.Lln2_nosh:
	s_mov_b32 s55, 0x40000
.Lln2_poll0:
	global_load_dwordx4 v[226:229], v247, s[34:35] sc1
	v_add_u32_e32 v251, 0x18000, v247
	global_load_dwordx4 v[230:233], v251, s[34:35] sc1
	v_add_u32_e32 v251, 0x30000, v247
	global_load_dwordx4 v[234:237], v251, s[34:35] sc1
	v_add_u32_e32 v251, 0x48000, v247
	global_load_dwordx4 v[238:241], v251, s[34:35] sc1
	v_add_u32_e32 v251, 0x60000, v247
	global_load_dwordx4 v[206:209], v251, s[34:35] sc1
	v_add_u32_e32 v251, 0x78000, v247
	global_load_dwordx4 v[210:213], v251, s[34:35] sc1
	v_add_u32_e32 v251, 0x90000, v247
	global_load_dwordx4 v[214:217], v251, s[34:35] sc1
	v_add_u32_e32 v251, 0xa8000, v247
	global_load_dwordx4 v[218:221], v251, s[34:35] sc1
	s_waitcnt vmcnt(0)
	v_xor_b32_e32 v248, v249, v227
	v_xor_b32_e32 v222, v249, v229
	v_xor_b32_e32 v251, v249, v231
	v_or_b32_e32 v248, v248, v251
	v_xor_b32_e32 v251, v249, v233
	v_or_b32_e32 v222, v222, v251
	v_xor_b32_e32 v251, v249, v235
	v_or_b32_e32 v248, v248, v251
	v_xor_b32_e32 v251, v249, v237
	v_or_b32_e32 v222, v222, v251
	v_xor_b32_e32 v251, v249, v239
	v_or_b32_e32 v248, v248, v251
	v_xor_b32_e32 v251, v249, v241
	v_or_b32_e32 v222, v222, v251
	v_xor_b32_e32 v251, v249, v207
	v_or_b32_e32 v248, v248, v251
	v_xor_b32_e32 v251, v249, v209
	v_or_b32_e32 v222, v222, v251
	v_xor_b32_e32 v251, v249, v211
	v_or_b32_e32 v248, v248, v251
	v_xor_b32_e32 v251, v249, v213
	v_or_b32_e32 v222, v222, v251
	v_xor_b32_e32 v251, v249, v215
	v_or_b32_e32 v248, v248, v251
	v_xor_b32_e32 v251, v249, v217
	v_or_b32_e32 v222, v222, v251
	v_xor_b32_e32 v251, v249, v219
	v_or_b32_e32 v248, v248, v251
	v_xor_b32_e32 v251, v249, v221
	v_or_b32_e32 v222, v222, v251
	v_or_b32_e32 v248, v248, v222
	v_cmp_ne_u32_e32 vcc, 0, v248
	s_cbranch_vccz .Lln2_pok0
	s_sleep 2
	s_add_i32 s55, s55, -1
	s_cmp_lg_u32 s55, 0
	s_cbranch_scc1 .Lln2_poll0
.Lln2_pok0:
	v_add_f32_e32 v250, 0, v226
	v_add_f32_e32 v252, 0, v228
	v_add_f32_e32 v250, v250, v230
	v_add_f32_e32 v252, v252, v232
	v_add_f32_e32 v250, v250, v234
	v_add_f32_e32 v252, v252, v236
	v_add_f32_e32 v250, v250, v238
	v_add_f32_e32 v252, v252, v240
	v_add_f32_e32 v250, v250, v206
	v_add_f32_e32 v252, v252, v208
	v_add_f32_e32 v250, v250, v210
	v_add_f32_e32 v252, v252, v212
	v_add_f32_e32 v250, v250, v214
	v_add_f32_e32 v252, v252, v216
	v_add_f32_e32 v250, v250, v218
	v_add_f32_e32 v252, v252, v220
	s_mov_b32 s55, 0x40000
.Lln2_poll1:
	v_add_u32_e32 v251, 0xc0000, v247
	global_load_dwordx4 v[226:229], v251, s[34:35] sc1
	v_add_u32_e32 v251, 0xd8000, v247
	global_load_dwordx4 v[230:233], v251, s[34:35] sc1
	v_add_u32_e32 v251, 0xf0000, v247
	global_load_dwordx4 v[234:237], v251, s[34:35] sc1
	v_add_u32_e32 v251, 0x108000, v247
	global_load_dwordx4 v[238:241], v251, s[34:35] sc1
	v_add_u32_e32 v251, 0x120000, v247
	global_load_dwordx4 v[206:209], v251, s[34:35] sc1
	v_add_u32_e32 v251, 0x138000, v247
	global_load_dwordx4 v[210:213], v251, s[34:35] sc1
	v_add_u32_e32 v251, 0x150000, v247
	global_load_dwordx4 v[214:217], v251, s[34:35] sc1
	v_add_u32_e32 v251, 0x168000, v247
	global_load_dwordx4 v[218:221], v251, s[34:35] sc1
	s_waitcnt vmcnt(0)
	v_xor_b32_e32 v248, v249, v227
	v_xor_b32_e32 v222, v249, v229
	v_xor_b32_e32 v251, v249, v231
	v_or_b32_e32 v248, v248, v251
	v_xor_b32_e32 v251, v249, v233
	v_or_b32_e32 v222, v222, v251
	v_xor_b32_e32 v251, v249, v235
	v_or_b32_e32 v248, v248, v251
	v_xor_b32_e32 v251, v249, v237
	v_or_b32_e32 v222, v222, v251
	v_xor_b32_e32 v251, v249, v239
	v_or_b32_e32 v248, v248, v251
	v_xor_b32_e32 v251, v249, v241
	v_or_b32_e32 v222, v222, v251
	v_xor_b32_e32 v251, v249, v207
	v_or_b32_e32 v248, v248, v251
	v_xor_b32_e32 v251, v249, v209
	v_or_b32_e32 v222, v222, v251
	v_xor_b32_e32 v251, v249, v211
	v_or_b32_e32 v248, v248, v251
	v_xor_b32_e32 v251, v249, v213
	v_or_b32_e32 v222, v222, v251
	v_xor_b32_e32 v251, v249, v215
	v_or_b32_e32 v248, v248, v251
	v_xor_b32_e32 v251, v249, v217
	v_or_b32_e32 v222, v222, v251
	v_xor_b32_e32 v251, v249, v219
	v_or_b32_e32 v248, v248, v251
	v_xor_b32_e32 v251, v249, v221
	v_or_b32_e32 v222, v222, v251
	v_or_b32_e32 v248, v248, v222
	v_cmp_ne_u32_e32 vcc, 0, v248
	s_cbranch_vccz .Lln2_pok1
	s_sleep 2
	s_add_i32 s55, s55, -1
	s_cmp_lg_u32 s55, 0
	s_cbranch_scc1 .Lln2_poll1
.Lln2_pok1:
	v_add_f32_e32 v250, v250, v226
	v_add_f32_e32 v252, v252, v228
	v_add_f32_e32 v250, v250, v230
	v_add_f32_e32 v252, v252, v232
	v_add_f32_e32 v250, v250, v234
	v_add_f32_e32 v252, v252, v236
	v_add_f32_e32 v250, v250, v238
	v_add_f32_e32 v252, v252, v240
	v_add_f32_e32 v250, v250, v206
	v_add_f32_e32 v252, v252, v208
	v_add_f32_e32 v250, v250, v210
	v_add_f32_e32 v252, v252, v212
	v_add_f32_e32 v250, v250, v214
	v_add_f32_e32 v252, v252, v216
	v_add_f32_e32 v250, v250, v218
	v_add_f32_e32 v252, v252, v220
	s_cmp_eq_u32 s53, 3
	s_cbranch_scc1 .Lln2_nomod
	global_load_dwordx4 v[226:229], v246, s[22:23]
	global_load_dwordx4 v[230:233], v246, s[22:23] offset:64
	global_load_dwordx4 v[234:237], v246, s[22:23] offset:128
	global_load_dwordx4 v[238:241], v246, s[22:23] offset:192
.Lln2_nomod:
	v_mov_b32_e32 v206, v250
	v_mov_b32_e32 v207, v252
	v_mul_f32_e32 v208, 0x3a800000, v206
	v_mul_f32_e32 v209, v208, v208
	v_mov_b32_e32 v216, 0x3a800000
	v_fma_f32 v209, v207, v216, -v209
	v_max_f32_e32 v209, 0, v209
	v_add_f32_e32 v209, 0x3727c5ac, v209
	v_rsq_f32_e32 v209, v209
	v_mov_b32_e32 v210, v208
	v_mov_b32_e32 v211, v208
	v_mov_b32_e32 v214, v209
	v_mov_b32_e32 v215, v209
	s_nop 1
	v_permlane16_swap_b32_e32 v210, v211
	v_permlane16_swap_b32_e32 v214, v215
	v_mov_b32_e32 v212, v210
	v_mov_b32_e32 v213, v211
	v_mov_b32_e32 v216, v214
	v_mov_b32_e32 v217, v215
	s_nop 1
	v_permlane32_swap_b32_e32 v210, v212
	v_permlane32_swap_b32_e32 v211, v213
	v_permlane32_swap_b32_e32 v214, v216
	v_permlane32_swap_b32_e32 v215, v217
	s_cmp_eq_u32 s53, 3
	s_cselect_b32 s26, s92, s26
	s_cselect_b32 s27, s93, s27
	v_sub_f32_e32 v62, v62, v210
	v_sub_f32_e32 v63, v63, v210
	v_sub_f32_e32 v64, v64, v210
	v_sub_f32_e32 v65, v65, v210
	v_mul_f32_e32 v62, v214, v62
	v_mul_f32_e32 v63, v214, v63
	v_mul_f32_e32 v64, v214, v64
	v_mul_f32_e32 v65, v214, v65
	v_fma_f32 v62, v66, v62, v90
	v_fma_f32 v63, v67, v63, v91
	v_fma_f32 v64, v68, v64, v92
	v_fma_f32 v65, v69, v65, v93
	global_store_dwordx4 v242, v[62:65], s[26:27]
	v_sub_f32_e32 v86, v86, v210
	v_sub_f32_e32 v87, v87, v210
	v_sub_f32_e32 v88, v88, v210
	v_sub_f32_e32 v89, v89, v210
	v_mul_f32_e32 v86, v214, v86
	v_mul_f32_e32 v87, v214, v87
	v_mul_f32_e32 v88, v214, v88
	v_mul_f32_e32 v89, v214, v89
	v_fma_f32 v86, v74, v86, v94
	v_fma_f32 v87, v75, v87, v95
	v_fma_f32 v88, v76, v88, v96
	v_fma_f32 v89, v77, v89, v97
	global_store_dwordx4 v242, v[86:89], s[26:27] offset:64
	v_sub_f32_e32 v70, v70, v210
	v_sub_f32_e32 v71, v71, v210
	v_sub_f32_e32 v72, v72, v210
	v_sub_f32_e32 v73, v73, v210
	v_mul_f32_e32 v70, v214, v70
	v_mul_f32_e32 v71, v214, v71
	v_mul_f32_e32 v72, v214, v72
	v_mul_f32_e32 v73, v214, v73
	v_fma_f32 v70, v78, v70, v108
	v_fma_f32 v71, v79, v71, v109
	v_fma_f32 v72, v80, v72, v110
	v_fma_f32 v73, v81, v73, v111
	global_store_dwordx4 v242, v[70:73], s[26:27] offset:128
	v_sub_f32_e32 v176, v176, v210
	v_sub_f32_e32 v177, v177, v210
	v_sub_f32_e32 v178, v178, v210
	v_sub_f32_e32 v179, v179, v210
	v_mul_f32_e32 v176, v214, v176
	v_mul_f32_e32 v177, v214, v177
	v_mul_f32_e32 v178, v214, v178
	v_mul_f32_e32 v179, v214, v179
	v_fma_f32 v176, v82, v176, v172
	v_fma_f32 v177, v83, v177, v173
	v_fma_f32 v178, v84, v178, v174
	v_fma_f32 v179, v85, v179, v175
	global_store_dwordx4 v242, v[176:179], s[26:27] offset:192
	v_sub_f32_e32 v202, v202, v211
	v_sub_f32_e32 v203, v203, v211
	v_sub_f32_e32 v204, v204, v211
	v_sub_f32_e32 v205, v205, v211
	v_mul_f32_e32 v202, v215, v202
	v_mul_f32_e32 v203, v215, v203
	v_mul_f32_e32 v204, v215, v204
	v_mul_f32_e32 v205, v215, v205
	v_fma_f32 v202, v66, v202, v90
	v_fma_f32 v203, v67, v203, v91
	v_fma_f32 v204, v68, v204, v92
	v_fma_f32 v205, v69, v205, v93
	global_store_dwordx4 v243, v[202:205], s[26:27]
	v_sub_f32_e32 v54, v54, v211
	v_sub_f32_e32 v55, v55, v211
	v_sub_f32_e32 v56, v56, v211
	v_sub_f32_e32 v57, v57, v211
	v_mul_f32_e32 v54, v215, v54
	v_mul_f32_e32 v55, v215, v55
	v_mul_f32_e32 v56, v215, v56
	v_mul_f32_e32 v57, v215, v57
	v_fma_f32 v54, v74, v54, v94
	v_fma_f32 v55, v75, v55, v95
	v_fma_f32 v56, v76, v56, v96
	v_fma_f32 v57, v77, v57, v97
	global_store_dwordx4 v243, v[54:57], s[26:27] offset:64
	v_sub_f32_e32 v58, v58, v211
	v_sub_f32_e32 v59, v59, v211
	v_sub_f32_e32 v60, v60, v211
	v_sub_f32_e32 v61, v61, v211
	v_mul_f32_e32 v58, v215, v58
	v_mul_f32_e32 v59, v215, v59
	v_mul_f32_e32 v60, v215, v60
	v_mul_f32_e32 v61, v215, v61
	v_fma_f32 v58, v78, v58, v108
	v_fma_f32 v59, v79, v59, v109
	v_fma_f32 v60, v80, v60, v110
	v_fma_f32 v61, v81, v61, v111
	global_store_dwordx4 v243, v[58:61], s[26:27] offset:128
	v_sub_f32_e32 v34, v34, v211
	v_sub_f32_e32 v35, v35, v211
	v_sub_f32_e32 v36, v36, v211
	v_sub_f32_e32 v37, v37, v211
	v_mul_f32_e32 v34, v215, v34
	v_mul_f32_e32 v35, v215, v35
	v_mul_f32_e32 v36, v215, v36
	v_mul_f32_e32 v37, v215, v37
	v_fma_f32 v34, v82, v34, v172
	v_fma_f32 v35, v83, v35, v173
	v_fma_f32 v36, v84, v36, v174
	v_fma_f32 v37, v85, v37, v175
	global_store_dwordx4 v243, v[34:37], s[26:27] offset:192
	v_sub_f32_e32 v30, v30, v212
	v_sub_f32_e32 v31, v31, v212
	v_sub_f32_e32 v32, v32, v212
	v_sub_f32_e32 v33, v33, v212
	v_mul_f32_e32 v30, v216, v30
	v_mul_f32_e32 v31, v216, v31
	v_mul_f32_e32 v32, v216, v32
	v_mul_f32_e32 v33, v216, v33
	v_fma_f32 v30, v66, v30, v90
	v_fma_f32 v31, v67, v31, v91
	v_fma_f32 v32, v68, v32, v92
	v_fma_f32 v33, v69, v33, v93
	global_store_dwordx4 v244, v[30:33], s[26:27]
	v_sub_f32_e32 v26, v26, v212
	v_sub_f32_e32 v27, v27, v212
	v_sub_f32_e32 v28, v28, v212
	v_sub_f32_e32 v29, v29, v212
	v_mul_f32_e32 v26, v216, v26
	v_mul_f32_e32 v27, v216, v27
	v_mul_f32_e32 v28, v216, v28
	v_mul_f32_e32 v29, v216, v29
	v_fma_f32 v26, v74, v26, v94
	v_fma_f32 v27, v75, v27, v95
	v_fma_f32 v28, v76, v28, v96
	v_fma_f32 v29, v77, v29, v97
	global_store_dwordx4 v244, v[26:29], s[26:27] offset:64
	v_sub_f32_e32 v22, v22, v212
	v_sub_f32_e32 v23, v23, v212
	v_sub_f32_e32 v24, v24, v212
	v_sub_f32_e32 v25, v25, v212
	v_mul_f32_e32 v22, v216, v22
	v_mul_f32_e32 v23, v216, v23
	v_mul_f32_e32 v24, v216, v24
	v_mul_f32_e32 v25, v216, v25
	v_fma_f32 v22, v78, v22, v108
	v_fma_f32 v23, v79, v23, v109
	v_fma_f32 v24, v80, v24, v110
	v_fma_f32 v25, v81, v25, v111
	global_store_dwordx4 v244, v[22:25], s[26:27] offset:128
	v_sub_f32_e32 v18, v18, v212
	v_sub_f32_e32 v19, v19, v212
	v_sub_f32_e32 v20, v20, v212
	v_sub_f32_e32 v21, v21, v212
	v_mul_f32_e32 v18, v216, v18
	v_mul_f32_e32 v19, v216, v19
	v_mul_f32_e32 v20, v216, v20
	v_mul_f32_e32 v21, v216, v21
	v_fma_f32 v18, v82, v18, v172
	v_fma_f32 v19, v83, v19, v173
	v_fma_f32 v20, v84, v20, v174
	v_fma_f32 v21, v85, v21, v175
	global_store_dwordx4 v244, v[18:21], s[26:27] offset:192
	v_sub_f32_e32 v14, v14, v213
	v_sub_f32_e32 v15, v15, v213
	v_sub_f32_e32 v16, v16, v213
	v_sub_f32_e32 v17, v17, v213
	v_mul_f32_e32 v14, v217, v14
	v_mul_f32_e32 v15, v217, v15
	v_mul_f32_e32 v16, v217, v16
	v_mul_f32_e32 v17, v217, v17
	v_fma_f32 v14, v66, v14, v90
	v_fma_f32 v15, v67, v15, v91
	v_fma_f32 v16, v68, v16, v92
	v_fma_f32 v17, v69, v17, v93
	global_store_dwordx4 v245, v[14:17], s[26:27]
	v_sub_f32_e32 v10, v10, v213
	v_sub_f32_e32 v11, v11, v213
	v_sub_f32_e32 v12, v12, v213
	v_sub_f32_e32 v13, v13, v213
	v_mul_f32_e32 v10, v217, v10
	v_mul_f32_e32 v11, v217, v11
	v_mul_f32_e32 v12, v217, v12
	v_mul_f32_e32 v13, v217, v13
	v_fma_f32 v10, v74, v10, v94
	v_fma_f32 v11, v75, v11, v95
	v_fma_f32 v12, v76, v12, v96
	v_fma_f32 v13, v77, v13, v97
	global_store_dwordx4 v245, v[10:13], s[26:27] offset:64
	v_sub_f32_e32 v6, v6, v213
	v_sub_f32_e32 v7, v7, v213
	v_sub_f32_e32 v8, v8, v213
	v_sub_f32_e32 v9, v9, v213
	v_mul_f32_e32 v6, v217, v6
	v_mul_f32_e32 v7, v217, v7
	v_mul_f32_e32 v8, v217, v8
	v_mul_f32_e32 v9, v217, v9
	v_fma_f32 v6, v78, v6, v108
	v_fma_f32 v7, v79, v7, v109
	v_fma_f32 v8, v80, v8, v110
	v_fma_f32 v9, v81, v9, v111
	global_store_dwordx4 v245, v[6:9], s[26:27] offset:128
	v_sub_f32_e32 v2, v2, v213
	v_sub_f32_e32 v3, v3, v213
	v_sub_f32_e32 v4, v4, v213
	v_sub_f32_e32 v5, v5, v213
	v_mul_f32_e32 v2, v217, v2
	v_mul_f32_e32 v3, v217, v3
	v_mul_f32_e32 v4, v217, v4
	v_mul_f32_e32 v5, v217, v5
	v_fma_f32 v2, v82, v2, v172
	v_fma_f32 v3, v83, v3, v173
	v_fma_f32 v4, v84, v4, v174
	v_fma_f32 v5, v85, v5, v175
	global_store_dwordx4 v245, v[2:5], s[26:27] offset:192
	s_cmp_eq_u32 s53, 3
	s_cbranch_scc1 .Lln2_end
	s_add_u32 s34, s94, 0x7b48000
	s_addc_u32 s35, s95, 0
	s_waitcnt vmcnt(16)
	v_add_f32_e32 v226, 1.0, v226
	v_add_f32_e32 v227, 1.0, v227
	v_add_f32_e32 v228, 1.0, v228
	v_add_f32_e32 v229, 1.0, v229
	v_add_f32_e32 v230, 1.0, v230
	v_add_f32_e32 v231, 1.0, v231
	v_add_f32_e32 v232, 1.0, v232
	v_add_f32_e32 v233, 1.0, v233
	v_add_f32_e32 v234, 1.0, v234
	v_add_f32_e32 v235, 1.0, v235
	v_add_f32_e32 v236, 1.0, v236
	v_add_f32_e32 v237, 1.0, v237
	v_add_f32_e32 v238, 1.0, v238
	v_add_f32_e32 v239, 1.0, v239
	v_add_f32_e32 v240, 1.0, v240
	v_add_f32_e32 v241, 1.0, v241
	v_lshrrev_b32_e32 v218, 1, v242
	v_lshrrev_b32_e32 v219, 1, v243
	v_lshrrev_b32_e32 v220, 1, v244
	v_lshrrev_b32_e32 v221, 1, v245
	v_fma_f32 v62, v226, v62, v38
	v_fma_f32 v63, v227, v63, v39
	v_fma_f32 v64, v228, v64, v40
	v_fma_f32 v65, v229, v65, v41
	v_cvt_pk_bf16_f32 v62, v62, v63
	v_cvt_pk_bf16_f32 v63, v64, v65
	global_store_dwordx2 v218, v[62:63], s[34:35]
	v_fma_f32 v86, v230, v86, v42
	v_fma_f32 v87, v231, v87, v43
	v_fma_f32 v88, v232, v88, v44
	v_fma_f32 v89, v233, v89, v45
	v_cvt_pk_bf16_f32 v86, v86, v87
	v_cvt_pk_bf16_f32 v87, v88, v89
	global_store_dwordx2 v218, v[86:87], s[34:35] offset:32
	v_fma_f32 v70, v234, v70, v46
	v_fma_f32 v71, v235, v71, v47
	v_fma_f32 v72, v236, v72, v48
	v_fma_f32 v73, v237, v73, v49
	v_cvt_pk_bf16_f32 v70, v70, v71
	v_cvt_pk_bf16_f32 v71, v72, v73
	global_store_dwordx2 v218, v[70:71], s[34:35] offset:64
	v_fma_f32 v176, v238, v176, v50
	v_fma_f32 v177, v239, v177, v51
	v_fma_f32 v178, v240, v178, v52
	v_fma_f32 v179, v241, v179, v53
	v_cvt_pk_bf16_f32 v176, v176, v177
	v_cvt_pk_bf16_f32 v177, v178, v179
	global_store_dwordx2 v218, v[176:177], s[34:35] offset:96
	v_fma_f32 v202, v226, v202, v38
	v_fma_f32 v203, v227, v203, v39
	v_fma_f32 v204, v228, v204, v40
	v_fma_f32 v205, v229, v205, v41
	v_cvt_pk_bf16_f32 v202, v202, v203
	v_cvt_pk_bf16_f32 v203, v204, v205
	global_store_dwordx2 v219, v[202:203], s[34:35]
	v_fma_f32 v54, v230, v54, v42
	v_fma_f32 v55, v231, v55, v43
	v_fma_f32 v56, v232, v56, v44
	v_fma_f32 v57, v233, v57, v45
	v_cvt_pk_bf16_f32 v54, v54, v55
	v_cvt_pk_bf16_f32 v55, v56, v57
	global_store_dwordx2 v219, v[54:55], s[34:35] offset:32
	v_fma_f32 v58, v234, v58, v46
	v_fma_f32 v59, v235, v59, v47
	v_fma_f32 v60, v236, v60, v48
	v_fma_f32 v61, v237, v61, v49
	v_cvt_pk_bf16_f32 v58, v58, v59
	v_cvt_pk_bf16_f32 v59, v60, v61
	global_store_dwordx2 v219, v[58:59], s[34:35] offset:64
	v_fma_f32 v34, v238, v34, v50
	v_fma_f32 v35, v239, v35, v51
	v_fma_f32 v36, v240, v36, v52
	v_fma_f32 v37, v241, v37, v53
	v_cvt_pk_bf16_f32 v34, v34, v35
	v_cvt_pk_bf16_f32 v35, v36, v37
	global_store_dwordx2 v219, v[34:35], s[34:35] offset:96
	v_fma_f32 v30, v226, v30, v38
	v_fma_f32 v31, v227, v31, v39
	v_fma_f32 v32, v228, v32, v40
	v_fma_f32 v33, v229, v33, v41
	v_cvt_pk_bf16_f32 v30, v30, v31
	v_cvt_pk_bf16_f32 v31, v32, v33
	global_store_dwordx2 v220, v[30:31], s[34:35]
	v_fma_f32 v26, v230, v26, v42
	v_fma_f32 v27, v231, v27, v43
	v_fma_f32 v28, v232, v28, v44
	v_fma_f32 v29, v233, v29, v45
	v_cvt_pk_bf16_f32 v26, v26, v27
	v_cvt_pk_bf16_f32 v27, v28, v29
	global_store_dwordx2 v220, v[26:27], s[34:35] offset:32
	v_fma_f32 v22, v234, v22, v46
	v_fma_f32 v23, v235, v23, v47
	v_fma_f32 v24, v236, v24, v48
	v_fma_f32 v25, v237, v25, v49
	v_cvt_pk_bf16_f32 v22, v22, v23
	v_cvt_pk_bf16_f32 v23, v24, v25
	global_store_dwordx2 v220, v[22:23], s[34:35] offset:64
	v_fma_f32 v18, v238, v18, v50
	v_fma_f32 v19, v239, v19, v51
	v_fma_f32 v20, v240, v20, v52
	v_fma_f32 v21, v241, v21, v53
	v_cvt_pk_bf16_f32 v18, v18, v19
	v_cvt_pk_bf16_f32 v19, v20, v21
	global_store_dwordx2 v220, v[18:19], s[34:35] offset:96
	v_fma_f32 v14, v226, v14, v38
	v_fma_f32 v15, v227, v15, v39
	v_fma_f32 v16, v228, v16, v40
	v_fma_f32 v17, v229, v17, v41
	v_cvt_pk_bf16_f32 v14, v14, v15
	v_cvt_pk_bf16_f32 v15, v16, v17
	global_store_dwordx2 v221, v[14:15], s[34:35]
	v_fma_f32 v10, v230, v10, v42
	v_fma_f32 v11, v231, v11, v43
	v_fma_f32 v12, v232, v12, v44
	v_fma_f32 v13, v233, v13, v45
	v_cvt_pk_bf16_f32 v10, v10, v11
	v_cvt_pk_bf16_f32 v11, v12, v13
	global_store_dwordx2 v221, v[10:11], s[34:35] offset:32
	v_fma_f32 v6, v234, v6, v46
	v_fma_f32 v7, v235, v7, v47
	v_fma_f32 v8, v236, v8, v48
	v_fma_f32 v9, v237, v9, v49
	v_cvt_pk_bf16_f32 v6, v6, v7
	v_cvt_pk_bf16_f32 v7, v8, v9
	global_store_dwordx2 v221, v[6:7], s[34:35] offset:64
	v_fma_f32 v2, v238, v2, v50
	v_fma_f32 v3, v239, v3, v51
	v_fma_f32 v4, v240, v4, v52
	v_fma_f32 v5, v241, v5, v53
	v_cvt_pk_bf16_f32 v2, v2, v3
	v_cvt_pk_bf16_f32 v3, v4, v5
	global_store_dwordx2 v221, v[2:3], s[34:35] offset:96
